# out-projection residual epilogue (E3 and O4): accumulators lane-permuted (ds_bpermute) so a quad covers 32 contiguous bytes, residual hi/lo loads issued ahead in a rolling pipeline, saddr addressing
# speedup vs baseline: 1.0416x; 1.0416x over previous
; __device__ __forceinline__ float bflo(unsigned v) { return __uint_as_float(v << 16); }
; __device__ __forceinline__ float bfhi(unsigned v) { return __uint_as_float(v & 0xffff0000u); }
; template <int EPI, int TI>
; __device__ __forceinline__ void gemm_epilogue(const WS& ws, const f32x4 (&acc)[4][TI], const float (&rs)[TI], int tok0, int n0,
;                                               int wm, int wn, int lr, int lq, bool dry) {
;     ...
;   } else {
; #pragma unroll
;     for (int ni = 0; ni < 4; ++ni)
; #pragma unroll
;       for (int ti = 0; ti < TI; ++ti) {
;         if (!(ti < 4 || (lr == 0 && (ni >> 1) == wn))) continue;
;         const size_t off = (size_t)(ti < 4 ? tokr(ti) : tok0 + 128) * 1024 + nw + ni * 16 + 4 * lq;
;         const u32x2 hi = *(const u32x2*)(ws.HHI + off), lo = *(const u32x2*)(ws.HLO + off);
;         const float h0 = bflo(hi.x) + bflo(lo.x) + acc[ni][ti][0], h1 = bfhi(hi.x) + bfhi(lo.x) + acc[ni][ti][1];
;         const float h2 = bflo(hi.y) + bflo(lo.y) + acc[ni][ti][2], h3 = bfhi(hi.y) + bfhi(lo.y) + acc[ni][ti][3];
;         u32x2 nh; nh.x = cvt_pk_bf16(h0, h1); nh.y = cvt_pk_bf16(h2, h3);
;         u32x2 nl; nl.x = cvt_pk_bf16(h0 - bflo(nh.x), h1 - bfhi(nh.x)); nl.y = cvt_pk_bf16(h2 - bflo(nh.y), h3 - bfhi(nh.y));
;         if (!dry) { *(u32x2*)(ws.HHI + off) = nh; *(u32x2*)(ws.HLO + off) = nl; }
;       }
.LBB0_971:
	s_waitcnt lgkmcnt(0)
	v_mbcnt_lo_u32_b32 v13, -1, 0
	v_mbcnt_hi_u32_b32 v13, -1, v13
	s_add_i32 s5, s4, 0x80
	v_and_b32_e32 v14, 3, v13
	v_lshrrev_b32_e32 v13, 2, v13
	s_lshl_b32 s5, s5, 11
	v_lshl_add_u32 v15, v14, 4, v13
	v_and_b32_e32 v247, 64, v184
	v_lshlrev_b32_e32 v15, 2, v15
	v_add3_u32 v13, s4, v247, v13
	v_lshl_add_u32 v247, s6, 7, v183
	s_mov_b64 s[6:7], exec
	v_lshl_add_u32 v14, v14, 2, v247
	v_or_b32_e32 v247, v247, v172
	v_lshlrev_b32_e32 v14, 1, v14
	v_lshlrev_b32_e32 v247, 1, v247
	v_lshl_add_u32 v242, v13, 11, v14
	v_add_u32_e32 v246, s5, v247
	v_add_u32_e32 v243, 0x8000, v242
	v_add_u32_e32 v244, 0x10000, v242
	v_add_u32_e32 v245, 0x18000, v242
	s_and_b64 exec, s[6:7], s[42:43]
	global_load_dwordx2 v[204:205], v246, s[44:45]
	global_load_dwordx2 v[206:207], v246, s[52:53]
	global_load_dwordx2 v[208:209], v246, s[44:45] offset:32
	global_load_dwordx2 v[210:211], v246, s[52:53] offset:32
	s_and_b64 exec, s[6:7], s[54:55]
	global_load_dwordx2 v[212:213], v246, s[44:45] offset:64
	global_load_dwordx2 v[214:215], v246, s[52:53] offset:64
	global_load_dwordx2 v[216:217], v246, s[44:45] offset:96
	global_load_dwordx2 v[218:219], v246, s[52:53] offset:96
	s_mov_b64 exec, s[6:7]
	global_load_dwordx2 v[140:141], v242, s[44:45]
	global_load_dwordx2 v[142:143], v242, s[52:53]
	global_load_dwordx2 v[144:145], v242, s[44:45] offset:32
	global_load_dwordx2 v[146:147], v242, s[52:53] offset:32
	global_load_dwordx2 v[148:149], v242, s[44:45] offset:64
	global_load_dwordx2 v[150:151], v242, s[52:53] offset:64
	global_load_dwordx2 v[152:153], v242, s[44:45] offset:96
	global_load_dwordx2 v[154:155], v242, s[52:53] offset:96
	global_load_dwordx2 v[156:157], v243, s[44:45]
	global_load_dwordx2 v[158:159], v243, s[52:53]
	global_load_dwordx2 v[160:161], v243, s[44:45] offset:32
	global_load_dwordx2 v[162:163], v243, s[52:53] offset:32
	ds_bpermute_b32 v136, v15, v136
	ds_bpermute_b32 v137, v15, v137
	ds_bpermute_b32 v138, v15, v138
	ds_bpermute_b32 v139, v15, v139
	ds_bpermute_b32 v120, v15, v120
	ds_bpermute_b32 v121, v15, v121
	ds_bpermute_b32 v122, v15, v122
	ds_bpermute_b32 v123, v15, v123
	ds_bpermute_b32 v100, v15, v100
	ds_bpermute_b32 v101, v15, v101
	ds_bpermute_b32 v102, v15, v102
	ds_bpermute_b32 v103, v15, v103
	s_waitcnt vmcnt(10)
	s_waitcnt lgkmcnt(8)
	v_lshlrev_b32_e32 v248, 16, v140
	v_and_b32_e32 v249, 0xffff0000, v140
	v_lshlrev_b32_e32 v252, 16, v142
	v_and_b32_e32 v253, 0xffff0000, v142
	v_lshlrev_b32_e32 v250, 16, v141
	v_and_b32_e32 v251, 0xffff0000, v141
	v_lshlrev_b32_e32 v254, 16, v143
	v_and_b32_e32 v255, 0xffff0000, v143
	v_pk_add_f32 v[248:249], v[248:249], v[252:253]
	v_pk_add_f32 v[250:251], v[250:251], v[254:255]
	v_pk_add_f32 v[136:137], v[136:137], v[248:249]
	v_pk_add_f32 v[138:139], v[138:139], v[250:251]
	v_cvt_pk_bf16_f32 v140, v136, v137
	v_cvt_pk_bf16_f32 v141, v138, v139
	v_lshlrev_b32_e32 v248, 16, v140
	v_and_b32_e32 v249, 0xffff0000, v140
	v_lshlrev_b32_e32 v250, 16, v141
	v_and_b32_e32 v251, 0xffff0000, v141
	v_pk_add_f32 v[136:137], v[136:137], v[248:249] neg_lo:[0,1] neg_hi:[0,1]
	v_pk_add_f32 v[138:139], v[138:139], v[250:251] neg_lo:[0,1] neg_hi:[0,1]
	v_cvt_pk_bf16_f32 v142, v136, v137
	v_cvt_pk_bf16_f32 v143, v138, v139
	global_store_dwordx2 v242, v[140:141], s[44:45]
	global_store_dwordx2 v242, v[142:143], s[52:53]
	global_load_dwordx2 v[140:141], v243, s[44:45] offset:64
	global_load_dwordx2 v[142:143], v243, s[52:53] offset:64
	ds_bpermute_b32 v80, v15, v80
	ds_bpermute_b32 v81, v15, v81
	ds_bpermute_b32 v82, v15, v82
	ds_bpermute_b32 v83, v15, v83
	s_waitcnt vmcnt(12)
	s_waitcnt lgkmcnt(8)
	v_lshlrev_b32_e32 v248, 16, v144
	v_and_b32_e32 v249, 0xffff0000, v144
	v_lshlrev_b32_e32 v252, 16, v146
	v_and_b32_e32 v253, 0xffff0000, v146
	v_lshlrev_b32_e32 v250, 16, v145
	v_and_b32_e32 v251, 0xffff0000, v145
	v_lshlrev_b32_e32 v254, 16, v147
	v_and_b32_e32 v255, 0xffff0000, v147
	v_pk_add_f32 v[248:249], v[248:249], v[252:253]
	v_pk_add_f32 v[250:251], v[250:251], v[254:255]
	v_pk_add_f32 v[120:121], v[120:121], v[248:249]
	v_pk_add_f32 v[122:123], v[122:123], v[250:251]
	v_cvt_pk_bf16_f32 v144, v120, v121
	v_cvt_pk_bf16_f32 v145, v122, v123
	v_lshlrev_b32_e32 v248, 16, v144
	v_and_b32_e32 v249, 0xffff0000, v144
	v_lshlrev_b32_e32 v250, 16, v145
	v_and_b32_e32 v251, 0xffff0000, v145
	v_pk_add_f32 v[120:121], v[120:121], v[248:249] neg_lo:[0,1] neg_hi:[0,1]
	v_pk_add_f32 v[122:123], v[122:123], v[250:251] neg_lo:[0,1] neg_hi:[0,1]
	v_cvt_pk_bf16_f32 v146, v120, v121
	v_cvt_pk_bf16_f32 v147, v122, v123
	global_store_dwordx2 v242, v[144:145], s[44:45] offset:32
	global_store_dwordx2 v242, v[146:147], s[52:53] offset:32
	global_load_dwordx2 v[144:145], v243, s[44:45] offset:96
	global_load_dwordx2 v[146:147], v243, s[52:53] offset:96
	ds_bpermute_b32 v132, v15, v132
	ds_bpermute_b32 v133, v15, v133
	ds_bpermute_b32 v134, v15, v134
	ds_bpermute_b32 v135, v15, v135
	s_waitcnt vmcnt(14)
	s_waitcnt lgkmcnt(8)
	v_lshlrev_b32_e32 v248, 16, v148
	v_and_b32_e32 v249, 0xffff0000, v148
	v_lshlrev_b32_e32 v252, 16, v150
	v_and_b32_e32 v253, 0xffff0000, v150
	v_lshlrev_b32_e32 v250, 16, v149
	v_and_b32_e32 v251, 0xffff0000, v149
	v_lshlrev_b32_e32 v254, 16, v151
	v_and_b32_e32 v255, 0xffff0000, v151
	v_pk_add_f32 v[248:249], v[248:249], v[252:253]
	v_pk_add_f32 v[250:251], v[250:251], v[254:255]
	v_pk_add_f32 v[100:101], v[100:101], v[248:249]
	v_pk_add_f32 v[102:103], v[102:103], v[250:251]
	v_cvt_pk_bf16_f32 v148, v100, v101
	v_cvt_pk_bf16_f32 v149, v102, v103
	v_lshlrev_b32_e32 v248, 16, v148
	v_and_b32_e32 v249, 0xffff0000, v148
	v_lshlrev_b32_e32 v250, 16, v149
	v_and_b32_e32 v251, 0xffff0000, v149
	v_pk_add_f32 v[100:101], v[100:101], v[248:249] neg_lo:[0,1] neg_hi:[0,1]
	v_pk_add_f32 v[102:103], v[102:103], v[250:251] neg_lo:[0,1] neg_hi:[0,1]
	v_cvt_pk_bf16_f32 v150, v100, v101
	v_cvt_pk_bf16_f32 v151, v102, v103
	global_store_dwordx2 v242, v[148:149], s[44:45] offset:64
	global_store_dwordx2 v242, v[150:151], s[52:53] offset:64
	global_load_dwordx2 v[148:149], v244, s[44:45]
	global_load_dwordx2 v[150:151], v244, s[52:53]
	ds_bpermute_b32 v116, v15, v116
	ds_bpermute_b32 v117, v15, v117
	ds_bpermute_b32 v118, v15, v118
	ds_bpermute_b32 v119, v15, v119
	s_waitcnt vmcnt(16)
; __device__ __forceinline__ float bflo(unsigned v) { return __uint_as_float(v << 16); }
; __device__ __forceinline__ float bfhi(unsigned v) { return __uint_as_float(v & 0xffff0000u); }
; template <int EPI, int TI>
; __device__ __forceinline__ void gemm_epilogue(const WS& ws, const f32x4 (&acc)[4][TI], const float (&rs)[TI], int tok0, int n0,
;                                               int wm, int wn, int lr, int lq, bool dry) {
;     ...
;   } else {
; #pragma unroll
;     for (int ni = 0; ni < 4; ++ni)
; #pragma unroll
;       for (int ti = 0; ti < TI; ++ti) {
;         if (!(ti < 4 || (lr == 0 && (ni >> 1) == wn))) continue;
;         const size_t off = (size_t)(ti < 4 ? tokr(ti) : tok0 + 128) * 1024 + nw + ni * 16 + 4 * lq;
;         const u32x2 hi = *(const u32x2*)(ws.HHI + off), lo = *(const u32x2*)(ws.HLO + off);
;         const float h0 = bflo(hi.x) + bflo(lo.x) + acc[ni][ti][0], h1 = bfhi(hi.x) + bfhi(lo.x) + acc[ni][ti][1];
;         const float h2 = bflo(hi.y) + bflo(lo.y) + acc[ni][ti][2], h3 = bfhi(hi.y) + bfhi(lo.y) + acc[ni][ti][3];
;         u32x2 nh; nh.x = cvt_pk_bf16(h0, h1); nh.y = cvt_pk_bf16(h2, h3);
;         u32x2 nl; nl.x = cvt_pk_bf16(h0 - bflo(nh.x), h1 - bfhi(nh.x)); nl.y = cvt_pk_bf16(h2 - bflo(nh.y), h3 - bfhi(nh.y));
;         if (!dry) { *(u32x2*)(ws.HHI + off) = nh; *(u32x2*)(ws.HLO + off) = nl; }
;       }
	s_waitcnt lgkmcnt(8)
	v_lshlrev_b32_e32 v248, 16, v152
	v_and_b32_e32 v249, 0xffff0000, v152
	v_lshlrev_b32_e32 v252, 16, v154
	v_and_b32_e32 v253, 0xffff0000, v154
	v_lshlrev_b32_e32 v250, 16, v153
	v_and_b32_e32 v251, 0xffff0000, v153
	v_lshlrev_b32_e32 v254, 16, v155
	v_and_b32_e32 v255, 0xffff0000, v155
	v_pk_add_f32 v[248:249], v[248:249], v[252:253]
	v_pk_add_f32 v[250:251], v[250:251], v[254:255]
	v_pk_add_f32 v[80:81], v[80:81], v[248:249]
	v_pk_add_f32 v[82:83], v[82:83], v[250:251]
	v_cvt_pk_bf16_f32 v152, v80, v81
	v_cvt_pk_bf16_f32 v153, v82, v83
	v_lshlrev_b32_e32 v248, 16, v152
	v_and_b32_e32 v249, 0xffff0000, v152
	v_lshlrev_b32_e32 v250, 16, v153
	v_and_b32_e32 v251, 0xffff0000, v153
	v_pk_add_f32 v[80:81], v[80:81], v[248:249] neg_lo:[0,1] neg_hi:[0,1]
	v_pk_add_f32 v[82:83], v[82:83], v[250:251] neg_lo:[0,1] neg_hi:[0,1]
	v_cvt_pk_bf16_f32 v154, v80, v81
	v_cvt_pk_bf16_f32 v155, v82, v83
	global_store_dwordx2 v242, v[152:153], s[44:45] offset:96
	global_store_dwordx2 v242, v[154:155], s[52:53] offset:96
	global_load_dwordx2 v[152:153], v244, s[44:45] offset:32
	global_load_dwordx2 v[154:155], v244, s[52:53] offset:32
	ds_bpermute_b32 v96, v15, v96
	ds_bpermute_b32 v97, v15, v97
	ds_bpermute_b32 v98, v15, v98
	ds_bpermute_b32 v99, v15, v99
	s_waitcnt vmcnt(18)
	s_waitcnt lgkmcnt(8)
	v_lshlrev_b32_e32 v248, 16, v156
	v_and_b32_e32 v249, 0xffff0000, v156
	v_lshlrev_b32_e32 v252, 16, v158
	v_and_b32_e32 v253, 0xffff0000, v158
	v_lshlrev_b32_e32 v250, 16, v157
	v_and_b32_e32 v251, 0xffff0000, v157
	v_lshlrev_b32_e32 v254, 16, v159
	v_and_b32_e32 v255, 0xffff0000, v159
	v_pk_add_f32 v[248:249], v[248:249], v[252:253]
	v_pk_add_f32 v[250:251], v[250:251], v[254:255]
	v_pk_add_f32 v[132:133], v[132:133], v[248:249]
	v_pk_add_f32 v[134:135], v[134:135], v[250:251]
	v_cvt_pk_bf16_f32 v156, v132, v133
	v_cvt_pk_bf16_f32 v157, v134, v135
	v_lshlrev_b32_e32 v248, 16, v156
	v_and_b32_e32 v249, 0xffff0000, v156
	v_lshlrev_b32_e32 v250, 16, v157
	v_and_b32_e32 v251, 0xffff0000, v157
	v_pk_add_f32 v[132:133], v[132:133], v[248:249] neg_lo:[0,1] neg_hi:[0,1]
	v_pk_add_f32 v[134:135], v[134:135], v[250:251] neg_lo:[0,1] neg_hi:[0,1]
	v_cvt_pk_bf16_f32 v158, v132, v133
	v_cvt_pk_bf16_f32 v159, v134, v135
	global_store_dwordx2 v243, v[156:157], s[44:45]
	global_store_dwordx2 v243, v[158:159], s[52:53]
	global_load_dwordx2 v[156:157], v244, s[44:45] offset:64
	global_load_dwordx2 v[158:159], v244, s[52:53] offset:64
	ds_bpermute_b32 v76, v15, v76
	ds_bpermute_b32 v77, v15, v77
	ds_bpermute_b32 v78, v15, v78
	ds_bpermute_b32 v79, v15, v79
	s_waitcnt vmcnt(20)
	s_waitcnt lgkmcnt(8)
	v_lshlrev_b32_e32 v248, 16, v160
	v_and_b32_e32 v249, 0xffff0000, v160
	v_lshlrev_b32_e32 v252, 16, v162
	v_and_b32_e32 v253, 0xffff0000, v162
	v_lshlrev_b32_e32 v250, 16, v161
	v_and_b32_e32 v251, 0xffff0000, v161
	v_lshlrev_b32_e32 v254, 16, v163
	v_and_b32_e32 v255, 0xffff0000, v163
	v_pk_add_f32 v[248:249], v[248:249], v[252:253]
	v_pk_add_f32 v[250:251], v[250:251], v[254:255]
	v_pk_add_f32 v[116:117], v[116:117], v[248:249]
	v_pk_add_f32 v[118:119], v[118:119], v[250:251]
	v_cvt_pk_bf16_f32 v160, v116, v117
	v_cvt_pk_bf16_f32 v161, v118, v119
	v_lshlrev_b32_e32 v248, 16, v160
	v_and_b32_e32 v249, 0xffff0000, v160
	v_lshlrev_b32_e32 v250, 16, v161
	v_and_b32_e32 v251, 0xffff0000, v161
	v_pk_add_f32 v[116:117], v[116:117], v[248:249] neg_lo:[0,1] neg_hi:[0,1]
	v_pk_add_f32 v[118:119], v[118:119], v[250:251] neg_lo:[0,1] neg_hi:[0,1]
	v_cvt_pk_bf16_f32 v162, v116, v117
	v_cvt_pk_bf16_f32 v163, v118, v119
	global_store_dwordx2 v243, v[160:161], s[44:45] offset:32
	global_store_dwordx2 v243, v[162:163], s[52:53] offset:32
	global_load_dwordx2 v[160:161], v244, s[44:45] offset:96
	global_load_dwordx2 v[162:163], v244, s[52:53] offset:96
	ds_bpermute_b32 v128, v15, v128
	ds_bpermute_b32 v129, v15, v129
	ds_bpermute_b32 v130, v15, v130
	ds_bpermute_b32 v131, v15, v131
	s_waitcnt vmcnt(20)
	s_waitcnt lgkmcnt(8)
	v_lshlrev_b32_e32 v248, 16, v140
	v_and_b32_e32 v249, 0xffff0000, v140
	v_lshlrev_b32_e32 v252, 16, v142
	v_and_b32_e32 v253, 0xffff0000, v142
	v_lshlrev_b32_e32 v250, 16, v141
	v_and_b32_e32 v251, 0xffff0000, v141
	v_lshlrev_b32_e32 v254, 16, v143
	v_and_b32_e32 v255, 0xffff0000, v143
	v_pk_add_f32 v[248:249], v[248:249], v[252:253]
	v_pk_add_f32 v[250:251], v[250:251], v[254:255]
	v_pk_add_f32 v[96:97], v[96:97], v[248:249]
	v_pk_add_f32 v[98:99], v[98:99], v[250:251]
	v_cvt_pk_bf16_f32 v140, v96, v97
	v_cvt_pk_bf16_f32 v141, v98, v99
	v_lshlrev_b32_e32 v248, 16, v140
	v_and_b32_e32 v249, 0xffff0000, v140
	v_lshlrev_b32_e32 v250, 16, v141
	v_and_b32_e32 v251, 0xffff0000, v141
	v_pk_add_f32 v[96:97], v[96:97], v[248:249] neg_lo:[0,1] neg_hi:[0,1]
	v_pk_add_f32 v[98:99], v[98:99], v[250:251] neg_lo:[0,1] neg_hi:[0,1]
	v_cvt_pk_bf16_f32 v142, v96, v97
	v_cvt_pk_bf16_f32 v143, v98, v99
	global_store_dwordx2 v243, v[140:141], s[44:45] offset:64
	global_store_dwordx2 v243, v[142:143], s[52:53] offset:64
	global_load_dwordx2 v[140:141], v245, s[44:45]
	global_load_dwordx2 v[142:143], v245, s[52:53]
	ds_bpermute_b32 v112, v15, v112
	ds_bpermute_b32 v113, v15, v113
	ds_bpermute_b32 v114, v15, v114
	ds_bpermute_b32 v115, v15, v115
	s_waitcnt vmcnt(20)
	s_waitcnt lgkmcnt(8)
; __device__ __forceinline__ float bflo(unsigned v) { return __uint_as_float(v << 16); }
; __device__ __forceinline__ float bfhi(unsigned v) { return __uint_as_float(v & 0xffff0000u); }
; template <int EPI, int TI>
; __device__ __forceinline__ void gemm_epilogue(const WS& ws, const f32x4 (&acc)[4][TI], const float (&rs)[TI], int tok0, int n0,
;                                               int wm, int wn, int lr, int lq, bool dry) {
;     ...
;   } else {
; #pragma unroll
;     for (int ni = 0; ni < 4; ++ni)
; #pragma unroll
;       for (int ti = 0; ti < TI; ++ti) {
;         if (!(ti < 4 || (lr == 0 && (ni >> 1) == wn))) continue;
;         const size_t off = (size_t)(ti < 4 ? tokr(ti) : tok0 + 128) * 1024 + nw + ni * 16 + 4 * lq;
;         const u32x2 hi = *(const u32x2*)(ws.HHI + off), lo = *(const u32x2*)(ws.HLO + off);
;         const float h0 = bflo(hi.x) + bflo(lo.x) + acc[ni][ti][0], h1 = bfhi(hi.x) + bfhi(lo.x) + acc[ni][ti][1];
;         const float h2 = bflo(hi.y) + bflo(lo.y) + acc[ni][ti][2], h3 = bfhi(hi.y) + bfhi(lo.y) + acc[ni][ti][3];
;         u32x2 nh; nh.x = cvt_pk_bf16(h0, h1); nh.y = cvt_pk_bf16(h2, h3);
;         u32x2 nl; nl.x = cvt_pk_bf16(h0 - bflo(nh.x), h1 - bfhi(nh.x)); nl.y = cvt_pk_bf16(h2 - bflo(nh.y), h3 - bfhi(nh.y));
;         if (!dry) { *(u32x2*)(ws.HHI + off) = nh; *(u32x2*)(ws.HLO + off) = nl; }
;       }
	v_lshlrev_b32_e32 v248, 16, v144
	v_and_b32_e32 v249, 0xffff0000, v144
	v_lshlrev_b32_e32 v252, 16, v146
	v_and_b32_e32 v253, 0xffff0000, v146
	v_lshlrev_b32_e32 v250, 16, v145
	v_and_b32_e32 v251, 0xffff0000, v145
	v_lshlrev_b32_e32 v254, 16, v147
	v_and_b32_e32 v255, 0xffff0000, v147
	v_pk_add_f32 v[248:249], v[248:249], v[252:253]
	v_pk_add_f32 v[250:251], v[250:251], v[254:255]
	v_pk_add_f32 v[76:77], v[76:77], v[248:249]
	v_pk_add_f32 v[78:79], v[78:79], v[250:251]
	v_cvt_pk_bf16_f32 v144, v76, v77
	v_cvt_pk_bf16_f32 v145, v78, v79
	v_lshlrev_b32_e32 v248, 16, v144
	v_and_b32_e32 v249, 0xffff0000, v144
	v_lshlrev_b32_e32 v250, 16, v145
	v_and_b32_e32 v251, 0xffff0000, v145
	v_pk_add_f32 v[76:77], v[76:77], v[248:249] neg_lo:[0,1] neg_hi:[0,1]
	v_pk_add_f32 v[78:79], v[78:79], v[250:251] neg_lo:[0,1] neg_hi:[0,1]
	v_cvt_pk_bf16_f32 v146, v76, v77
	v_cvt_pk_bf16_f32 v147, v78, v79
	global_store_dwordx2 v243, v[144:145], s[44:45] offset:96
	global_store_dwordx2 v243, v[146:147], s[52:53] offset:96
	global_load_dwordx2 v[144:145], v245, s[44:45] offset:32
	global_load_dwordx2 v[146:147], v245, s[52:53] offset:32
	ds_bpermute_b32 v92, v15, v92
	ds_bpermute_b32 v93, v15, v93
	ds_bpermute_b32 v94, v15, v94
	ds_bpermute_b32 v95, v15, v95
	s_waitcnt vmcnt(20)
	s_waitcnt lgkmcnt(8)
	v_lshlrev_b32_e32 v248, 16, v148
	v_and_b32_e32 v249, 0xffff0000, v148
	v_lshlrev_b32_e32 v252, 16, v150
	v_and_b32_e32 v253, 0xffff0000, v150
	v_lshlrev_b32_e32 v250, 16, v149
	v_and_b32_e32 v251, 0xffff0000, v149
	v_lshlrev_b32_e32 v254, 16, v151
	v_and_b32_e32 v255, 0xffff0000, v151
	v_pk_add_f32 v[248:249], v[248:249], v[252:253]
	v_pk_add_f32 v[250:251], v[250:251], v[254:255]
	v_pk_add_f32 v[128:129], v[128:129], v[248:249]
	v_pk_add_f32 v[130:131], v[130:131], v[250:251]
	v_cvt_pk_bf16_f32 v148, v128, v129
	v_cvt_pk_bf16_f32 v149, v130, v131
	v_lshlrev_b32_e32 v248, 16, v148
	v_and_b32_e32 v249, 0xffff0000, v148
	v_lshlrev_b32_e32 v250, 16, v149
	v_and_b32_e32 v251, 0xffff0000, v149
	v_pk_add_f32 v[128:129], v[128:129], v[248:249] neg_lo:[0,1] neg_hi:[0,1]
	v_pk_add_f32 v[130:131], v[130:131], v[250:251] neg_lo:[0,1] neg_hi:[0,1]
	v_cvt_pk_bf16_f32 v150, v128, v129
	v_cvt_pk_bf16_f32 v151, v130, v131
	global_store_dwordx2 v244, v[148:149], s[44:45]
	global_store_dwordx2 v244, v[150:151], s[52:53]
	global_load_dwordx2 v[148:149], v245, s[44:45] offset:64
	global_load_dwordx2 v[150:151], v245, s[52:53] offset:64
	ds_bpermute_b32 v72, v15, v72
	ds_bpermute_b32 v73, v15, v73
	ds_bpermute_b32 v74, v15, v74
	ds_bpermute_b32 v75, v15, v75
	s_waitcnt vmcnt(20)
	s_waitcnt lgkmcnt(8)
	v_lshlrev_b32_e32 v248, 16, v152
	v_and_b32_e32 v249, 0xffff0000, v152
	v_lshlrev_b32_e32 v252, 16, v154
	v_and_b32_e32 v253, 0xffff0000, v154
	v_lshlrev_b32_e32 v250, 16, v153
	v_and_b32_e32 v251, 0xffff0000, v153
	v_lshlrev_b32_e32 v254, 16, v155
	v_and_b32_e32 v255, 0xffff0000, v155
	v_pk_add_f32 v[248:249], v[248:249], v[252:253]
	v_pk_add_f32 v[250:251], v[250:251], v[254:255]
	v_pk_add_f32 v[112:113], v[112:113], v[248:249]
	v_pk_add_f32 v[114:115], v[114:115], v[250:251]
	v_cvt_pk_bf16_f32 v152, v112, v113
	v_cvt_pk_bf16_f32 v153, v114, v115
	v_lshlrev_b32_e32 v248, 16, v152
	v_and_b32_e32 v249, 0xffff0000, v152
	v_lshlrev_b32_e32 v250, 16, v153
	v_and_b32_e32 v251, 0xffff0000, v153
	v_pk_add_f32 v[112:113], v[112:113], v[248:249] neg_lo:[0,1] neg_hi:[0,1]
	v_pk_add_f32 v[114:115], v[114:115], v[250:251] neg_lo:[0,1] neg_hi:[0,1]
	v_cvt_pk_bf16_f32 v154, v112, v113
	v_cvt_pk_bf16_f32 v155, v114, v115
	global_store_dwordx2 v244, v[152:153], s[44:45] offset:32
	global_store_dwordx2 v244, v[154:155], s[52:53] offset:32
	global_load_dwordx2 v[152:153], v245, s[44:45] offset:96
	global_load_dwordx2 v[154:155], v245, s[52:53] offset:96
	ds_bpermute_b32 v124, v15, v124
	ds_bpermute_b32 v125, v15, v125
	ds_bpermute_b32 v126, v15, v126
	ds_bpermute_b32 v127, v15, v127
	s_waitcnt vmcnt(20)
	s_waitcnt lgkmcnt(8)
	v_lshlrev_b32_e32 v248, 16, v156
	v_and_b32_e32 v249, 0xffff0000, v156
	v_lshlrev_b32_e32 v252, 16, v158
	v_and_b32_e32 v253, 0xffff0000, v158
	v_lshlrev_b32_e32 v250, 16, v157
	v_and_b32_e32 v251, 0xffff0000, v157
	v_lshlrev_b32_e32 v254, 16, v159
	v_and_b32_e32 v255, 0xffff0000, v159
	v_pk_add_f32 v[248:249], v[248:249], v[252:253]
	v_pk_add_f32 v[250:251], v[250:251], v[254:255]
	v_pk_add_f32 v[92:93], v[92:93], v[248:249]
	v_pk_add_f32 v[94:95], v[94:95], v[250:251]
	v_cvt_pk_bf16_f32 v156, v92, v93
	v_cvt_pk_bf16_f32 v157, v94, v95
	v_lshlrev_b32_e32 v248, 16, v156
	v_and_b32_e32 v249, 0xffff0000, v156
	v_lshlrev_b32_e32 v250, 16, v157
	v_and_b32_e32 v251, 0xffff0000, v157
	v_pk_add_f32 v[92:93], v[92:93], v[248:249] neg_lo:[0,1] neg_hi:[0,1]
	v_pk_add_f32 v[94:95], v[94:95], v[250:251] neg_lo:[0,1] neg_hi:[0,1]
	v_cvt_pk_bf16_f32 v158, v92, v93
	v_cvt_pk_bf16_f32 v159, v94, v95
	global_store_dwordx2 v244, v[156:157], s[44:45] offset:64
	global_store_dwordx2 v244, v[158:159], s[52:53] offset:64
	ds_bpermute_b32 v104, v15, v104
	ds_bpermute_b32 v105, v15, v105
	ds_bpermute_b32 v106, v15, v106
	ds_bpermute_b32 v107, v15, v107
	s_waitcnt vmcnt(18)
	s_waitcnt lgkmcnt(8)
; __device__ __forceinline__ float bflo(unsigned v) { return __uint_as_float(v << 16); }
; __device__ __forceinline__ float bfhi(unsigned v) { return __uint_as_float(v & 0xffff0000u); }
; template <int EPI, int TI>
; __device__ __forceinline__ void gemm_epilogue(const WS& ws, const f32x4 (&acc)[4][TI], const float (&rs)[TI], int tok0, int n0,
;                                               int wm, int wn, int lr, int lq, bool dry) {
;     ...
;   } else {
; #pragma unroll
;     for (int ni = 0; ni < 4; ++ni)
; #pragma unroll
;       for (int ti = 0; ti < TI; ++ti) {
;         if (!(ti < 4 || (lr == 0 && (ni >> 1) == wn))) continue;
;         const size_t off = (size_t)(ti < 4 ? tokr(ti) : tok0 + 128) * 1024 + nw + ni * 16 + 4 * lq;
;         const u32x2 hi = *(const u32x2*)(ws.HHI + off), lo = *(const u32x2*)(ws.HLO + off);
;         const float h0 = bflo(hi.x) + bflo(lo.x) + acc[ni][ti][0], h1 = bfhi(hi.x) + bfhi(lo.x) + acc[ni][ti][1];
;         const float h2 = bflo(hi.y) + bflo(lo.y) + acc[ni][ti][2], h3 = bfhi(hi.y) + bfhi(lo.y) + acc[ni][ti][3];
;         u32x2 nh; nh.x = cvt_pk_bf16(h0, h1); nh.y = cvt_pk_bf16(h2, h3);
;         u32x2 nl; nl.x = cvt_pk_bf16(h0 - bflo(nh.x), h1 - bfhi(nh.x)); nl.y = cvt_pk_bf16(h2 - bflo(nh.y), h3 - bfhi(nh.y));
;         if (!dry) { *(u32x2*)(ws.HHI + off) = nh; *(u32x2*)(ws.HLO + off) = nl; }
;       }
	v_lshlrev_b32_e32 v248, 16, v160
	v_and_b32_e32 v249, 0xffff0000, v160
	v_lshlrev_b32_e32 v252, 16, v162
	v_and_b32_e32 v253, 0xffff0000, v162
	v_lshlrev_b32_e32 v250, 16, v161
	v_and_b32_e32 v251, 0xffff0000, v161
	v_lshlrev_b32_e32 v254, 16, v163
	v_and_b32_e32 v255, 0xffff0000, v163
	v_pk_add_f32 v[248:249], v[248:249], v[252:253]
	v_pk_add_f32 v[250:251], v[250:251], v[254:255]
	v_pk_add_f32 v[72:73], v[72:73], v[248:249]
	v_pk_add_f32 v[74:75], v[74:75], v[250:251]
	v_cvt_pk_bf16_f32 v160, v72, v73
	v_cvt_pk_bf16_f32 v161, v74, v75
	v_lshlrev_b32_e32 v248, 16, v160
	v_and_b32_e32 v249, 0xffff0000, v160
	v_lshlrev_b32_e32 v250, 16, v161
	v_and_b32_e32 v251, 0xffff0000, v161
	v_pk_add_f32 v[72:73], v[72:73], v[248:249] neg_lo:[0,1] neg_hi:[0,1]
	v_pk_add_f32 v[74:75], v[74:75], v[250:251] neg_lo:[0,1] neg_hi:[0,1]
	v_cvt_pk_bf16_f32 v162, v72, v73
	v_cvt_pk_bf16_f32 v163, v74, v75
	global_store_dwordx2 v244, v[160:161], s[44:45] offset:96
	global_store_dwordx2 v244, v[162:163], s[52:53] offset:96
	ds_bpermute_b32 v84, v15, v84
	ds_bpermute_b32 v85, v15, v85
	ds_bpermute_b32 v86, v15, v86
	ds_bpermute_b32 v87, v15, v87
	s_waitcnt vmcnt(16)
	s_waitcnt lgkmcnt(8)
	v_lshlrev_b32_e32 v248, 16, v140
	v_and_b32_e32 v249, 0xffff0000, v140
	v_lshlrev_b32_e32 v252, 16, v142
	v_and_b32_e32 v253, 0xffff0000, v142
	v_lshlrev_b32_e32 v250, 16, v141
	v_and_b32_e32 v251, 0xffff0000, v141
	v_lshlrev_b32_e32 v254, 16, v143
	v_and_b32_e32 v255, 0xffff0000, v143
	v_pk_add_f32 v[248:249], v[248:249], v[252:253]
	v_pk_add_f32 v[250:251], v[250:251], v[254:255]
	v_pk_add_f32 v[124:125], v[124:125], v[248:249]
	v_pk_add_f32 v[126:127], v[126:127], v[250:251]
	v_cvt_pk_bf16_f32 v140, v124, v125
	v_cvt_pk_bf16_f32 v141, v126, v127
	v_lshlrev_b32_e32 v248, 16, v140
	v_and_b32_e32 v249, 0xffff0000, v140
	v_lshlrev_b32_e32 v250, 16, v141
	v_and_b32_e32 v251, 0xffff0000, v141
	v_pk_add_f32 v[124:125], v[124:125], v[248:249] neg_lo:[0,1] neg_hi:[0,1]
	v_pk_add_f32 v[126:127], v[126:127], v[250:251] neg_lo:[0,1] neg_hi:[0,1]
	v_cvt_pk_bf16_f32 v142, v124, v125
	v_cvt_pk_bf16_f32 v143, v126, v127
	global_store_dwordx2 v245, v[140:141], s[44:45]
	global_store_dwordx2 v245, v[142:143], s[52:53]
	ds_bpermute_b32 v68, v15, v68
	ds_bpermute_b32 v69, v15, v69
	ds_bpermute_b32 v70, v15, v70
	ds_bpermute_b32 v71, v15, v71
	s_waitcnt vmcnt(14)
	s_waitcnt lgkmcnt(8)
	v_lshlrev_b32_e32 v248, 16, v144
	v_and_b32_e32 v249, 0xffff0000, v144
	v_lshlrev_b32_e32 v252, 16, v146
	v_and_b32_e32 v253, 0xffff0000, v146
	v_lshlrev_b32_e32 v250, 16, v145
	v_and_b32_e32 v251, 0xffff0000, v145
	v_lshlrev_b32_e32 v254, 16, v147
	v_and_b32_e32 v255, 0xffff0000, v147
	v_pk_add_f32 v[248:249], v[248:249], v[252:253]
	v_pk_add_f32 v[250:251], v[250:251], v[254:255]
	v_pk_add_f32 v[104:105], v[104:105], v[248:249]
	v_pk_add_f32 v[106:107], v[106:107], v[250:251]
	v_cvt_pk_bf16_f32 v144, v104, v105
	v_cvt_pk_bf16_f32 v145, v106, v107
	v_lshlrev_b32_e32 v248, 16, v144
	v_and_b32_e32 v249, 0xffff0000, v144
	v_lshlrev_b32_e32 v250, 16, v145
	v_and_b32_e32 v251, 0xffff0000, v145
	v_pk_add_f32 v[104:105], v[104:105], v[248:249] neg_lo:[0,1] neg_hi:[0,1]
	v_pk_add_f32 v[106:107], v[106:107], v[250:251] neg_lo:[0,1] neg_hi:[0,1]
	v_cvt_pk_bf16_f32 v146, v104, v105
	v_cvt_pk_bf16_f32 v147, v106, v107
	global_store_dwordx2 v245, v[144:145], s[44:45] offset:32
	global_store_dwordx2 v245, v[146:147], s[52:53] offset:32
	s_waitcnt vmcnt(12)
	s_waitcnt lgkmcnt(4)
	v_lshlrev_b32_e32 v248, 16, v148
	v_and_b32_e32 v249, 0xffff0000, v148
	v_lshlrev_b32_e32 v252, 16, v150
	v_and_b32_e32 v253, 0xffff0000, v150
	v_lshlrev_b32_e32 v250, 16, v149
	v_and_b32_e32 v251, 0xffff0000, v149
	v_lshlrev_b32_e32 v254, 16, v151
	v_and_b32_e32 v255, 0xffff0000, v151
	v_pk_add_f32 v[248:249], v[248:249], v[252:253]
	v_pk_add_f32 v[250:251], v[250:251], v[254:255]
	v_pk_add_f32 v[84:85], v[84:85], v[248:249]
	v_pk_add_f32 v[86:87], v[86:87], v[250:251]
	v_cvt_pk_bf16_f32 v148, v84, v85
	v_cvt_pk_bf16_f32 v149, v86, v87
	v_lshlrev_b32_e32 v248, 16, v148
	v_and_b32_e32 v249, 0xffff0000, v148
	v_lshlrev_b32_e32 v250, 16, v149
	v_and_b32_e32 v251, 0xffff0000, v149
	v_pk_add_f32 v[84:85], v[84:85], v[248:249] neg_lo:[0,1] neg_hi:[0,1]
	v_pk_add_f32 v[86:87], v[86:87], v[250:251] neg_lo:[0,1] neg_hi:[0,1]
	v_cvt_pk_bf16_f32 v150, v84, v85
	v_cvt_pk_bf16_f32 v151, v86, v87
	global_store_dwordx2 v245, v[148:149], s[44:45] offset:64
	global_store_dwordx2 v245, v[150:151], s[52:53] offset:64
	s_waitcnt vmcnt(10)
	s_waitcnt lgkmcnt(0)
; __device__ __forceinline__ float bflo(unsigned v) { return __uint_as_float(v << 16); }
; __device__ __forceinline__ float bfhi(unsigned v) { return __uint_as_float(v & 0xffff0000u); }
; template <int EPI, int TI>
; __device__ __forceinline__ void gemm_epilogue(const WS& ws, const f32x4 (&acc)[4][TI], const float (&rs)[TI], int tok0, int n0,
;                                               int wm, int wn, int lr, int lq, bool dry) {
;     ...
;   } else {
; #pragma unroll
;     for (int ni = 0; ni < 4; ++ni)
; #pragma unroll
;       for (int ti = 0; ti < TI; ++ti) {
;         if (!(ti < 4 || (lr == 0 && (ni >> 1) == wn))) continue;
;         const size_t off = (size_t)(ti < 4 ? tokr(ti) : tok0 + 128) * 1024 + nw + ni * 16 + 4 * lq;
;         const u32x2 hi = *(const u32x2*)(ws.HHI + off), lo = *(const u32x2*)(ws.HLO + off);
;         const float h0 = bflo(hi.x) + bflo(lo.x) + acc[ni][ti][0], h1 = bfhi(hi.x) + bfhi(lo.x) + acc[ni][ti][1];
;         const float h2 = bflo(hi.y) + bflo(lo.y) + acc[ni][ti][2], h3 = bfhi(hi.y) + bfhi(lo.y) + acc[ni][ti][3];
;         u32x2 nh; nh.x = cvt_pk_bf16(h0, h1); nh.y = cvt_pk_bf16(h2, h3);
;         u32x2 nl; nl.x = cvt_pk_bf16(h0 - bflo(nh.x), h1 - bfhi(nh.x)); nl.y = cvt_pk_bf16(h2 - bflo(nh.y), h3 - bfhi(nh.y));
;         if (!dry) { *(u32x2*)(ws.HHI + off) = nh; *(u32x2*)(ws.HLO + off) = nl; }
;       }
	v_lshlrev_b32_e32 v248, 16, v152
	v_and_b32_e32 v249, 0xffff0000, v152
	v_lshlrev_b32_e32 v252, 16, v154
	v_and_b32_e32 v253, 0xffff0000, v154
	v_lshlrev_b32_e32 v250, 16, v153
	v_and_b32_e32 v251, 0xffff0000, v153
	v_lshlrev_b32_e32 v254, 16, v155
	v_and_b32_e32 v255, 0xffff0000, v155
	v_pk_add_f32 v[248:249], v[248:249], v[252:253]
	v_pk_add_f32 v[250:251], v[250:251], v[254:255]
	v_pk_add_f32 v[68:69], v[68:69], v[248:249]
	v_pk_add_f32 v[70:71], v[70:71], v[250:251]
	v_cvt_pk_bf16_f32 v152, v68, v69
	v_cvt_pk_bf16_f32 v153, v70, v71
	v_lshlrev_b32_e32 v248, 16, v152
	v_and_b32_e32 v249, 0xffff0000, v152
	v_lshlrev_b32_e32 v250, 16, v153
	v_and_b32_e32 v251, 0xffff0000, v153
	v_pk_add_f32 v[68:69], v[68:69], v[248:249] neg_lo:[0,1] neg_hi:[0,1]
	v_pk_add_f32 v[70:71], v[70:71], v[250:251] neg_lo:[0,1] neg_hi:[0,1]
	v_cvt_pk_bf16_f32 v154, v68, v69
	v_cvt_pk_bf16_f32 v155, v70, v71
	global_store_dwordx2 v245, v[152:153], s[44:45] offset:96
	global_store_dwordx2 v245, v[154:155], s[52:53] offset:96
	s_and_b64 exec, s[6:7], s[42:43]
	s_waitcnt vmcnt(63)
	v_lshlrev_b32_e32 v248, 16, v204
	v_and_b32_e32 v249, 0xffff0000, v204
	v_lshlrev_b32_e32 v252, 16, v206
	v_and_b32_e32 v253, 0xffff0000, v206
	v_lshlrev_b32_e32 v250, 16, v205
	v_and_b32_e32 v251, 0xffff0000, v205
	v_lshlrev_b32_e32 v254, 16, v207
	v_and_b32_e32 v255, 0xffff0000, v207
	v_pk_add_f32 v[248:249], v[248:249], v[252:253]
	v_pk_add_f32 v[250:251], v[250:251], v[254:255]
	v_pk_add_f32 v[108:109], v[108:109], v[248:249]
	v_pk_add_f32 v[110:111], v[110:111], v[250:251]
	v_cvt_pk_bf16_f32 v204, v108, v109
	v_cvt_pk_bf16_f32 v205, v110, v111
	v_lshlrev_b32_e32 v248, 16, v204
	v_and_b32_e32 v249, 0xffff0000, v204
	v_lshlrev_b32_e32 v250, 16, v205
	v_and_b32_e32 v251, 0xffff0000, v205
	v_pk_add_f32 v[108:109], v[108:109], v[248:249] neg_lo:[0,1] neg_hi:[0,1]
	v_pk_add_f32 v[110:111], v[110:111], v[250:251] neg_lo:[0,1] neg_hi:[0,1]
	v_cvt_pk_bf16_f32 v206, v108, v109
	v_cvt_pk_bf16_f32 v207, v110, v111
	global_store_dwordx2 v246, v[204:205], s[44:45]
	global_store_dwordx2 v246, v[206:207], s[52:53]
	s_waitcnt vmcnt(63)
	v_lshlrev_b32_e32 v248, 16, v208
	v_and_b32_e32 v249, 0xffff0000, v208
	v_lshlrev_b32_e32 v252, 16, v210
	v_and_b32_e32 v253, 0xffff0000, v210
	v_lshlrev_b32_e32 v250, 16, v209
	v_and_b32_e32 v251, 0xffff0000, v209
	v_lshlrev_b32_e32 v254, 16, v211
	v_and_b32_e32 v255, 0xffff0000, v211
	v_pk_add_f32 v[248:249], v[248:249], v[252:253]
	v_pk_add_f32 v[250:251], v[250:251], v[254:255]
	v_pk_add_f32 v[88:89], v[88:89], v[248:249]
	v_pk_add_f32 v[90:91], v[90:91], v[250:251]
	v_cvt_pk_bf16_f32 v208, v88, v89
	v_cvt_pk_bf16_f32 v209, v90, v91
	v_lshlrev_b32_e32 v248, 16, v208
	v_and_b32_e32 v249, 0xffff0000, v208
	v_lshlrev_b32_e32 v250, 16, v209
	v_and_b32_e32 v251, 0xffff0000, v209
	v_pk_add_f32 v[88:89], v[88:89], v[248:249] neg_lo:[0,1] neg_hi:[0,1]
	v_pk_add_f32 v[90:91], v[90:91], v[250:251] neg_lo:[0,1] neg_hi:[0,1]
	v_cvt_pk_bf16_f32 v210, v88, v89
	v_cvt_pk_bf16_f32 v211, v90, v91
	global_store_dwordx2 v246, v[208:209], s[44:45] offset:32
	global_store_dwordx2 v246, v[210:211], s[52:53] offset:32
	s_and_b64 exec, s[6:7], s[54:55]
	s_waitcnt vmcnt(63)
	v_lshlrev_b32_e32 v248, 16, v212
	v_and_b32_e32 v249, 0xffff0000, v212
	v_lshlrev_b32_e32 v252, 16, v214
	v_and_b32_e32 v253, 0xffff0000, v214
	v_lshlrev_b32_e32 v250, 16, v213
	v_and_b32_e32 v251, 0xffff0000, v213
	v_lshlrev_b32_e32 v254, 16, v215
	v_and_b32_e32 v255, 0xffff0000, v215
	v_pk_add_f32 v[248:249], v[248:249], v[252:253]
	v_pk_add_f32 v[250:251], v[250:251], v[254:255]
	v_pk_add_f32 v[36:37], v[36:37], v[248:249]
	v_pk_add_f32 v[38:39], v[38:39], v[250:251]
	v_cvt_pk_bf16_f32 v212, v36, v37
	v_cvt_pk_bf16_f32 v213, v38, v39
	v_lshlrev_b32_e32 v248, 16, v212
	v_and_b32_e32 v249, 0xffff0000, v212
	v_lshlrev_b32_e32 v250, 16, v213
	v_and_b32_e32 v251, 0xffff0000, v213
	v_pk_add_f32 v[36:37], v[36:37], v[248:249] neg_lo:[0,1] neg_hi:[0,1]
	v_pk_add_f32 v[38:39], v[38:39], v[250:251] neg_lo:[0,1] neg_hi:[0,1]
	v_cvt_pk_bf16_f32 v214, v36, v37
	v_cvt_pk_bf16_f32 v215, v38, v39
	global_store_dwordx2 v246, v[212:213], s[44:45] offset:64
	global_store_dwordx2 v246, v[214:215], s[52:53] offset:64
	s_waitcnt vmcnt(63)
	v_lshlrev_b32_e32 v248, 16, v216
	v_and_b32_e32 v249, 0xffff0000, v216
	v_lshlrev_b32_e32 v252, 16, v218
	v_and_b32_e32 v253, 0xffff0000, v218
	v_lshlrev_b32_e32 v250, 16, v217
	v_and_b32_e32 v251, 0xffff0000, v217
	v_lshlrev_b32_e32 v254, 16, v219
	v_and_b32_e32 v255, 0xffff0000, v219
	v_pk_add_f32 v[248:249], v[248:249], v[252:253]
	v_pk_add_f32 v[250:251], v[250:251], v[254:255]
	v_pk_add_f32 v[32:33], v[32:33], v[248:249]
	v_pk_add_f32 v[34:35], v[34:35], v[250:251]
	v_cvt_pk_bf16_f32 v216, v32, v33
	v_cvt_pk_bf16_f32 v217, v34, v35
	v_lshlrev_b32_e32 v248, 16, v216
	v_and_b32_e32 v249, 0xffff0000, v216
	v_lshlrev_b32_e32 v250, 16, v217
	v_and_b32_e32 v251, 0xffff0000, v217
	v_pk_add_f32 v[32:33], v[32:33], v[248:249] neg_lo:[0,1] neg_hi:[0,1]
	v_pk_add_f32 v[34:35], v[34:35], v[250:251] neg_lo:[0,1] neg_hi:[0,1]
	v_cvt_pk_bf16_f32 v218, v32, v33
	v_cvt_pk_bf16_f32 v219, v34, v35
	global_store_dwordx2 v246, v[216:217], s[44:45] offset:96
	global_store_dwordx2 v246, v[218:219], s[52:53] offset:96
	s_mov_b64 exec, s[6:7]

; __device__ __forceinline__ float bflo(unsigned v) { return __uint_as_float(v << 16); }
; __device__ __forceinline__ float bfhi(unsigned v) { return __uint_as_float(v & 0xffff0000u); }
; template <int EPI, int TI>
; __device__ __forceinline__ void gemm_epilogue(const WS& ws, const f32x4 (&acc)[4][TI], const float (&rs)[TI], int tok0, int n0,
;                                               int wm, int wn, int lr, int lq, bool dry) {
;     ...
;   } else {
; #pragma unroll
;     for (int ni = 0; ni < 4; ++ni)
; #pragma unroll
;       for (int ti = 0; ti < TI; ++ti) {
;         if (!(ti < 4 || (lr == 0 && (ni >> 1) == wn))) continue;
;         const size_t off = (size_t)(ti < 4 ? tokr(ti) : tok0 + 128) * 1024 + nw + ni * 16 + 4 * lq;
;         const u32x2 hi = *(const u32x2*)(ws.HHI + off), lo = *(const u32x2*)(ws.HLO + off);
;         const float h0 = bflo(hi.x) + bflo(lo.x) + acc[ni][ti][0], h1 = bfhi(hi.x) + bfhi(lo.x) + acc[ni][ti][1];
;         const float h2 = bflo(hi.y) + bflo(lo.y) + acc[ni][ti][2], h3 = bfhi(hi.y) + bfhi(lo.y) + acc[ni][ti][3];
;         u32x2 nh; nh.x = cvt_pk_bf16(h0, h1); nh.y = cvt_pk_bf16(h2, h3);
;         u32x2 nl; nl.x = cvt_pk_bf16(h0 - bflo(nh.x), h1 - bfhi(nh.x)); nl.y = cvt_pk_bf16(h2 - bflo(nh.y), h3 - bfhi(nh.y));
;         if (!dry) { *(u32x2*)(ws.HHI + off) = nh; *(u32x2*)(ws.HLO + off) = nl; }
;       }
.LBB0_1812:
	s_waitcnt lgkmcnt(0)
	v_mbcnt_lo_u32_b32 v13, -1, 0
	v_mbcnt_hi_u32_b32 v13, -1, v13
	s_add_i32 s5, s4, 0x80
	v_and_b32_e32 v14, 3, v13
	v_lshrrev_b32_e32 v13, 2, v13
	s_lshl_b32 s5, s5, 11
	v_lshl_add_u32 v15, v14, 4, v13
	v_and_b32_e32 v247, 64, v184
	v_lshlrev_b32_e32 v15, 2, v15
	v_add3_u32 v13, s4, v247, v13
	v_lshl_add_u32 v247, s6, 7, v183
	s_mov_b64 s[6:7], exec
	v_lshl_add_u32 v14, v14, 2, v247
	v_or_b32_e32 v247, v247, v172
	v_lshlrev_b32_e32 v14, 1, v14
	v_lshlrev_b32_e32 v247, 1, v247
	v_lshl_add_u32 v242, v13, 11, v14
	v_add_u32_e32 v246, s5, v247
	v_add_u32_e32 v243, 0x8000, v242
	v_add_u32_e32 v244, 0x10000, v242
	v_add_u32_e32 v245, 0x18000, v242
	s_and_b64 exec, s[6:7], s[42:43]
	global_load_dwordx2 v[204:205], v246, s[44:45]
	global_load_dwordx2 v[206:207], v246, s[50:51]
	global_load_dwordx2 v[208:209], v246, s[44:45] offset:32
	global_load_dwordx2 v[210:211], v246, s[50:51] offset:32
	s_and_b64 exec, s[6:7], s[52:53]
	global_load_dwordx2 v[212:213], v246, s[44:45] offset:64
	global_load_dwordx2 v[214:215], v246, s[50:51] offset:64
	global_load_dwordx2 v[216:217], v246, s[44:45] offset:96
	global_load_dwordx2 v[218:219], v246, s[50:51] offset:96
	s_mov_b64 exec, s[6:7]
	global_load_dwordx2 v[140:141], v242, s[44:45]
	global_load_dwordx2 v[142:143], v242, s[50:51]
	global_load_dwordx2 v[144:145], v242, s[44:45] offset:32
	global_load_dwordx2 v[146:147], v242, s[50:51] offset:32
	global_load_dwordx2 v[148:149], v242, s[44:45] offset:64
	global_load_dwordx2 v[150:151], v242, s[50:51] offset:64
	global_load_dwordx2 v[152:153], v242, s[44:45] offset:96
	global_load_dwordx2 v[154:155], v242, s[50:51] offset:96
	global_load_dwordx2 v[156:157], v243, s[44:45]
	global_load_dwordx2 v[158:159], v243, s[50:51]
	global_load_dwordx2 v[160:161], v243, s[44:45] offset:32
	global_load_dwordx2 v[162:163], v243, s[50:51] offset:32
	ds_bpermute_b32 v136, v15, v136
	ds_bpermute_b32 v137, v15, v137
	ds_bpermute_b32 v138, v15, v138
	ds_bpermute_b32 v139, v15, v139
	ds_bpermute_b32 v120, v15, v120
	ds_bpermute_b32 v121, v15, v121
	ds_bpermute_b32 v122, v15, v122
	ds_bpermute_b32 v123, v15, v123
	ds_bpermute_b32 v100, v15, v100
	ds_bpermute_b32 v101, v15, v101
	ds_bpermute_b32 v102, v15, v102
	ds_bpermute_b32 v103, v15, v103
	s_waitcnt vmcnt(10)
	s_waitcnt lgkmcnt(8)
	v_lshlrev_b32_e32 v248, 16, v140
	v_and_b32_e32 v249, 0xffff0000, v140
	v_lshlrev_b32_e32 v252, 16, v142
	v_and_b32_e32 v253, 0xffff0000, v142
	v_lshlrev_b32_e32 v250, 16, v141
	v_and_b32_e32 v251, 0xffff0000, v141
	v_lshlrev_b32_e32 v254, 16, v143
	v_and_b32_e32 v255, 0xffff0000, v143
	v_pk_add_f32 v[248:249], v[248:249], v[252:253]
	v_pk_add_f32 v[250:251], v[250:251], v[254:255]
	v_pk_add_f32 v[136:137], v[136:137], v[248:249]
	v_pk_add_f32 v[138:139], v[138:139], v[250:251]
	v_cvt_pk_bf16_f32 v140, v136, v137
	v_cvt_pk_bf16_f32 v141, v138, v139
	v_lshlrev_b32_e32 v248, 16, v140
	v_and_b32_e32 v249, 0xffff0000, v140
	v_lshlrev_b32_e32 v250, 16, v141
	v_and_b32_e32 v251, 0xffff0000, v141
	v_pk_add_f32 v[136:137], v[136:137], v[248:249] neg_lo:[0,1] neg_hi:[0,1]
	v_pk_add_f32 v[138:139], v[138:139], v[250:251] neg_lo:[0,1] neg_hi:[0,1]
	v_cvt_pk_bf16_f32 v142, v136, v137
	v_cvt_pk_bf16_f32 v143, v138, v139
	global_store_dwordx2 v242, v[140:141], s[44:45]
	global_store_dwordx2 v242, v[142:143], s[50:51]
	global_load_dwordx2 v[140:141], v243, s[44:45] offset:64
	global_load_dwordx2 v[142:143], v243, s[50:51] offset:64
	ds_bpermute_b32 v80, v15, v80
	ds_bpermute_b32 v81, v15, v81
	ds_bpermute_b32 v82, v15, v82
	ds_bpermute_b32 v83, v15, v83
	s_waitcnt vmcnt(12)
	s_waitcnt lgkmcnt(8)
	v_lshlrev_b32_e32 v248, 16, v144
	v_and_b32_e32 v249, 0xffff0000, v144
	v_lshlrev_b32_e32 v252, 16, v146
	v_and_b32_e32 v253, 0xffff0000, v146
	v_lshlrev_b32_e32 v250, 16, v145
	v_and_b32_e32 v251, 0xffff0000, v145
	v_lshlrev_b32_e32 v254, 16, v147
	v_and_b32_e32 v255, 0xffff0000, v147
	v_pk_add_f32 v[248:249], v[248:249], v[252:253]
	v_pk_add_f32 v[250:251], v[250:251], v[254:255]
	v_pk_add_f32 v[120:121], v[120:121], v[248:249]
	v_pk_add_f32 v[122:123], v[122:123], v[250:251]
	v_cvt_pk_bf16_f32 v144, v120, v121
	v_cvt_pk_bf16_f32 v145, v122, v123
	v_lshlrev_b32_e32 v248, 16, v144
	v_and_b32_e32 v249, 0xffff0000, v144
	v_lshlrev_b32_e32 v250, 16, v145
	v_and_b32_e32 v251, 0xffff0000, v145
	v_pk_add_f32 v[120:121], v[120:121], v[248:249] neg_lo:[0,1] neg_hi:[0,1]
	v_pk_add_f32 v[122:123], v[122:123], v[250:251] neg_lo:[0,1] neg_hi:[0,1]
	v_cvt_pk_bf16_f32 v146, v120, v121
	v_cvt_pk_bf16_f32 v147, v122, v123
	global_store_dwordx2 v242, v[144:145], s[44:45] offset:32
	global_store_dwordx2 v242, v[146:147], s[50:51] offset:32
	global_load_dwordx2 v[144:145], v243, s[44:45] offset:96
	global_load_dwordx2 v[146:147], v243, s[50:51] offset:96
	ds_bpermute_b32 v132, v15, v132
	ds_bpermute_b32 v133, v15, v133
	ds_bpermute_b32 v134, v15, v134
	ds_bpermute_b32 v135, v15, v135
	s_waitcnt vmcnt(14)
	s_waitcnt lgkmcnt(8)
	v_lshlrev_b32_e32 v248, 16, v148
	v_and_b32_e32 v249, 0xffff0000, v148
	v_lshlrev_b32_e32 v252, 16, v150
	v_and_b32_e32 v253, 0xffff0000, v150
	v_lshlrev_b32_e32 v250, 16, v149
	v_and_b32_e32 v251, 0xffff0000, v149
	v_lshlrev_b32_e32 v254, 16, v151
	v_and_b32_e32 v255, 0xffff0000, v151
	v_pk_add_f32 v[248:249], v[248:249], v[252:253]
	v_pk_add_f32 v[250:251], v[250:251], v[254:255]
	v_pk_add_f32 v[100:101], v[100:101], v[248:249]
	v_pk_add_f32 v[102:103], v[102:103], v[250:251]
	v_cvt_pk_bf16_f32 v148, v100, v101
	v_cvt_pk_bf16_f32 v149, v102, v103
	v_lshlrev_b32_e32 v248, 16, v148
	v_and_b32_e32 v249, 0xffff0000, v148
	v_lshlrev_b32_e32 v250, 16, v149
	v_and_b32_e32 v251, 0xffff0000, v149
	v_pk_add_f32 v[100:101], v[100:101], v[248:249] neg_lo:[0,1] neg_hi:[0,1]
	v_pk_add_f32 v[102:103], v[102:103], v[250:251] neg_lo:[0,1] neg_hi:[0,1]
	v_cvt_pk_bf16_f32 v150, v100, v101
	v_cvt_pk_bf16_f32 v151, v102, v103
	global_store_dwordx2 v242, v[148:149], s[44:45] offset:64
	global_store_dwordx2 v242, v[150:151], s[50:51] offset:64
	global_load_dwordx2 v[148:149], v244, s[44:45]
	global_load_dwordx2 v[150:151], v244, s[50:51]
	ds_bpermute_b32 v116, v15, v116
	ds_bpermute_b32 v117, v15, v117
	ds_bpermute_b32 v118, v15, v118
	ds_bpermute_b32 v119, v15, v119
	s_waitcnt vmcnt(16)
; __device__ __forceinline__ float bflo(unsigned v) { return __uint_as_float(v << 16); }
; __device__ __forceinline__ float bfhi(unsigned v) { return __uint_as_float(v & 0xffff0000u); }
; template <int EPI, int TI>
; __device__ __forceinline__ void gemm_epilogue(const WS& ws, const f32x4 (&acc)[4][TI], const float (&rs)[TI], int tok0, int n0,
;                                               int wm, int wn, int lr, int lq, bool dry) {
;     ...
;   } else {
; #pragma unroll
;     for (int ni = 0; ni < 4; ++ni)
; #pragma unroll
;       for (int ti = 0; ti < TI; ++ti) {
;         if (!(ti < 4 || (lr == 0 && (ni >> 1) == wn))) continue;
;         const size_t off = (size_t)(ti < 4 ? tokr(ti) : tok0 + 128) * 1024 + nw + ni * 16 + 4 * lq;
;         const u32x2 hi = *(const u32x2*)(ws.HHI + off), lo = *(const u32x2*)(ws.HLO + off);
;         const float h0 = bflo(hi.x) + bflo(lo.x) + acc[ni][ti][0], h1 = bfhi(hi.x) + bfhi(lo.x) + acc[ni][ti][1];
;         const float h2 = bflo(hi.y) + bflo(lo.y) + acc[ni][ti][2], h3 = bfhi(hi.y) + bfhi(lo.y) + acc[ni][ti][3];
;         u32x2 nh; nh.x = cvt_pk_bf16(h0, h1); nh.y = cvt_pk_bf16(h2, h3);
;         u32x2 nl; nl.x = cvt_pk_bf16(h0 - bflo(nh.x), h1 - bfhi(nh.x)); nl.y = cvt_pk_bf16(h2 - bflo(nh.y), h3 - bfhi(nh.y));
;         if (!dry) { *(u32x2*)(ws.HHI + off) = nh; *(u32x2*)(ws.HLO + off) = nl; }
;       }
	s_waitcnt lgkmcnt(8)
	v_lshlrev_b32_e32 v248, 16, v152
	v_and_b32_e32 v249, 0xffff0000, v152
	v_lshlrev_b32_e32 v252, 16, v154
	v_and_b32_e32 v253, 0xffff0000, v154
	v_lshlrev_b32_e32 v250, 16, v153
	v_and_b32_e32 v251, 0xffff0000, v153
	v_lshlrev_b32_e32 v254, 16, v155
	v_and_b32_e32 v255, 0xffff0000, v155
	v_pk_add_f32 v[248:249], v[248:249], v[252:253]
	v_pk_add_f32 v[250:251], v[250:251], v[254:255]
	v_pk_add_f32 v[80:81], v[80:81], v[248:249]
	v_pk_add_f32 v[82:83], v[82:83], v[250:251]
	v_cvt_pk_bf16_f32 v152, v80, v81
	v_cvt_pk_bf16_f32 v153, v82, v83
	v_lshlrev_b32_e32 v248, 16, v152
	v_and_b32_e32 v249, 0xffff0000, v152
	v_lshlrev_b32_e32 v250, 16, v153
	v_and_b32_e32 v251, 0xffff0000, v153
	v_pk_add_f32 v[80:81], v[80:81], v[248:249] neg_lo:[0,1] neg_hi:[0,1]
	v_pk_add_f32 v[82:83], v[82:83], v[250:251] neg_lo:[0,1] neg_hi:[0,1]
	v_cvt_pk_bf16_f32 v154, v80, v81
	v_cvt_pk_bf16_f32 v155, v82, v83
	global_store_dwordx2 v242, v[152:153], s[44:45] offset:96
	global_store_dwordx2 v242, v[154:155], s[50:51] offset:96
	global_load_dwordx2 v[152:153], v244, s[44:45] offset:32
	global_load_dwordx2 v[154:155], v244, s[50:51] offset:32
	ds_bpermute_b32 v96, v15, v96
	ds_bpermute_b32 v97, v15, v97
	ds_bpermute_b32 v98, v15, v98
	ds_bpermute_b32 v99, v15, v99
	s_waitcnt vmcnt(18)
	s_waitcnt lgkmcnt(8)
	v_lshlrev_b32_e32 v248, 16, v156
	v_and_b32_e32 v249, 0xffff0000, v156
	v_lshlrev_b32_e32 v252, 16, v158
	v_and_b32_e32 v253, 0xffff0000, v158
	v_lshlrev_b32_e32 v250, 16, v157
	v_and_b32_e32 v251, 0xffff0000, v157
	v_lshlrev_b32_e32 v254, 16, v159
	v_and_b32_e32 v255, 0xffff0000, v159
	v_pk_add_f32 v[248:249], v[248:249], v[252:253]
	v_pk_add_f32 v[250:251], v[250:251], v[254:255]
	v_pk_add_f32 v[132:133], v[132:133], v[248:249]
	v_pk_add_f32 v[134:135], v[134:135], v[250:251]
	v_cvt_pk_bf16_f32 v156, v132, v133
	v_cvt_pk_bf16_f32 v157, v134, v135
	v_lshlrev_b32_e32 v248, 16, v156
	v_and_b32_e32 v249, 0xffff0000, v156
	v_lshlrev_b32_e32 v250, 16, v157
	v_and_b32_e32 v251, 0xffff0000, v157
	v_pk_add_f32 v[132:133], v[132:133], v[248:249] neg_lo:[0,1] neg_hi:[0,1]
	v_pk_add_f32 v[134:135], v[134:135], v[250:251] neg_lo:[0,1] neg_hi:[0,1]
	v_cvt_pk_bf16_f32 v158, v132, v133
	v_cvt_pk_bf16_f32 v159, v134, v135
	global_store_dwordx2 v243, v[156:157], s[44:45]
	global_store_dwordx2 v243, v[158:159], s[50:51]
	global_load_dwordx2 v[156:157], v244, s[44:45] offset:64
	global_load_dwordx2 v[158:159], v244, s[50:51] offset:64
	ds_bpermute_b32 v76, v15, v76
	ds_bpermute_b32 v77, v15, v77
	ds_bpermute_b32 v78, v15, v78
	ds_bpermute_b32 v79, v15, v79
	s_waitcnt vmcnt(20)
	s_waitcnt lgkmcnt(8)
	v_lshlrev_b32_e32 v248, 16, v160
	v_and_b32_e32 v249, 0xffff0000, v160
	v_lshlrev_b32_e32 v252, 16, v162
	v_and_b32_e32 v253, 0xffff0000, v162
	v_lshlrev_b32_e32 v250, 16, v161
	v_and_b32_e32 v251, 0xffff0000, v161
	v_lshlrev_b32_e32 v254, 16, v163
	v_and_b32_e32 v255, 0xffff0000, v163
	v_pk_add_f32 v[248:249], v[248:249], v[252:253]
	v_pk_add_f32 v[250:251], v[250:251], v[254:255]
	v_pk_add_f32 v[116:117], v[116:117], v[248:249]
	v_pk_add_f32 v[118:119], v[118:119], v[250:251]
	v_cvt_pk_bf16_f32 v160, v116, v117
	v_cvt_pk_bf16_f32 v161, v118, v119
	v_lshlrev_b32_e32 v248, 16, v160
	v_and_b32_e32 v249, 0xffff0000, v160
	v_lshlrev_b32_e32 v250, 16, v161
	v_and_b32_e32 v251, 0xffff0000, v161
	v_pk_add_f32 v[116:117], v[116:117], v[248:249] neg_lo:[0,1] neg_hi:[0,1]
	v_pk_add_f32 v[118:119], v[118:119], v[250:251] neg_lo:[0,1] neg_hi:[0,1]
	v_cvt_pk_bf16_f32 v162, v116, v117
	v_cvt_pk_bf16_f32 v163, v118, v119
	global_store_dwordx2 v243, v[160:161], s[44:45] offset:32
	global_store_dwordx2 v243, v[162:163], s[50:51] offset:32
	global_load_dwordx2 v[160:161], v244, s[44:45] offset:96
	global_load_dwordx2 v[162:163], v244, s[50:51] offset:96
	ds_bpermute_b32 v128, v15, v128
	ds_bpermute_b32 v129, v15, v129
	ds_bpermute_b32 v130, v15, v130
	ds_bpermute_b32 v131, v15, v131
	s_waitcnt vmcnt(20)
	s_waitcnt lgkmcnt(8)
	v_lshlrev_b32_e32 v248, 16, v140
	v_and_b32_e32 v249, 0xffff0000, v140
	v_lshlrev_b32_e32 v252, 16, v142
	v_and_b32_e32 v253, 0xffff0000, v142
	v_lshlrev_b32_e32 v250, 16, v141
	v_and_b32_e32 v251, 0xffff0000, v141
	v_lshlrev_b32_e32 v254, 16, v143
	v_and_b32_e32 v255, 0xffff0000, v143
	v_pk_add_f32 v[248:249], v[248:249], v[252:253]
	v_pk_add_f32 v[250:251], v[250:251], v[254:255]
	v_pk_add_f32 v[96:97], v[96:97], v[248:249]
	v_pk_add_f32 v[98:99], v[98:99], v[250:251]
	v_cvt_pk_bf16_f32 v140, v96, v97
	v_cvt_pk_bf16_f32 v141, v98, v99
	v_lshlrev_b32_e32 v248, 16, v140
	v_and_b32_e32 v249, 0xffff0000, v140
	v_lshlrev_b32_e32 v250, 16, v141
	v_and_b32_e32 v251, 0xffff0000, v141
	v_pk_add_f32 v[96:97], v[96:97], v[248:249] neg_lo:[0,1] neg_hi:[0,1]
	v_pk_add_f32 v[98:99], v[98:99], v[250:251] neg_lo:[0,1] neg_hi:[0,1]
	v_cvt_pk_bf16_f32 v142, v96, v97
	v_cvt_pk_bf16_f32 v143, v98, v99
	global_store_dwordx2 v243, v[140:141], s[44:45] offset:64
	global_store_dwordx2 v243, v[142:143], s[50:51] offset:64
	global_load_dwordx2 v[140:141], v245, s[44:45]
	global_load_dwordx2 v[142:143], v245, s[50:51]
	ds_bpermute_b32 v112, v15, v112
	ds_bpermute_b32 v113, v15, v113
	ds_bpermute_b32 v114, v15, v114
	ds_bpermute_b32 v115, v15, v115
	s_waitcnt vmcnt(20)
	s_waitcnt lgkmcnt(8)
; __device__ __forceinline__ float bflo(unsigned v) { return __uint_as_float(v << 16); }
; __device__ __forceinline__ float bfhi(unsigned v) { return __uint_as_float(v & 0xffff0000u); }
; template <int EPI, int TI>
; __device__ __forceinline__ void gemm_epilogue(const WS& ws, const f32x4 (&acc)[4][TI], const float (&rs)[TI], int tok0, int n0,
;                                               int wm, int wn, int lr, int lq, bool dry) {
;     ...
;   } else {
; #pragma unroll
;     for (int ni = 0; ni < 4; ++ni)
; #pragma unroll
;       for (int ti = 0; ti < TI; ++ti) {
;         if (!(ti < 4 || (lr == 0 && (ni >> 1) == wn))) continue;
;         const size_t off = (size_t)(ti < 4 ? tokr(ti) : tok0 + 128) * 1024 + nw + ni * 16 + 4 * lq;
;         const u32x2 hi = *(const u32x2*)(ws.HHI + off), lo = *(const u32x2*)(ws.HLO + off);
;         const float h0 = bflo(hi.x) + bflo(lo.x) + acc[ni][ti][0], h1 = bfhi(hi.x) + bfhi(lo.x) + acc[ni][ti][1];
;         const float h2 = bflo(hi.y) + bflo(lo.y) + acc[ni][ti][2], h3 = bfhi(hi.y) + bfhi(lo.y) + acc[ni][ti][3];
;         u32x2 nh; nh.x = cvt_pk_bf16(h0, h1); nh.y = cvt_pk_bf16(h2, h3);
;         u32x2 nl; nl.x = cvt_pk_bf16(h0 - bflo(nh.x), h1 - bfhi(nh.x)); nl.y = cvt_pk_bf16(h2 - bflo(nh.y), h3 - bfhi(nh.y));
;         if (!dry) { *(u32x2*)(ws.HHI + off) = nh; *(u32x2*)(ws.HLO + off) = nl; }
;       }
	v_lshlrev_b32_e32 v248, 16, v144
	v_and_b32_e32 v249, 0xffff0000, v144
	v_lshlrev_b32_e32 v252, 16, v146
	v_and_b32_e32 v253, 0xffff0000, v146
	v_lshlrev_b32_e32 v250, 16, v145
	v_and_b32_e32 v251, 0xffff0000, v145
	v_lshlrev_b32_e32 v254, 16, v147
	v_and_b32_e32 v255, 0xffff0000, v147
	v_pk_add_f32 v[248:249], v[248:249], v[252:253]
	v_pk_add_f32 v[250:251], v[250:251], v[254:255]
	v_pk_add_f32 v[76:77], v[76:77], v[248:249]
	v_pk_add_f32 v[78:79], v[78:79], v[250:251]
	v_cvt_pk_bf16_f32 v144, v76, v77
	v_cvt_pk_bf16_f32 v145, v78, v79
	v_lshlrev_b32_e32 v248, 16, v144
	v_and_b32_e32 v249, 0xffff0000, v144
	v_lshlrev_b32_e32 v250, 16, v145
	v_and_b32_e32 v251, 0xffff0000, v145
	v_pk_add_f32 v[76:77], v[76:77], v[248:249] neg_lo:[0,1] neg_hi:[0,1]
	v_pk_add_f32 v[78:79], v[78:79], v[250:251] neg_lo:[0,1] neg_hi:[0,1]
	v_cvt_pk_bf16_f32 v146, v76, v77
	v_cvt_pk_bf16_f32 v147, v78, v79
	global_store_dwordx2 v243, v[144:145], s[44:45] offset:96
	global_store_dwordx2 v243, v[146:147], s[50:51] offset:96
	global_load_dwordx2 v[144:145], v245, s[44:45] offset:32
	global_load_dwordx2 v[146:147], v245, s[50:51] offset:32
	ds_bpermute_b32 v92, v15, v92
	ds_bpermute_b32 v93, v15, v93
	ds_bpermute_b32 v94, v15, v94
	ds_bpermute_b32 v95, v15, v95
	s_waitcnt vmcnt(20)
	s_waitcnt lgkmcnt(8)
	v_lshlrev_b32_e32 v248, 16, v148
	v_and_b32_e32 v249, 0xffff0000, v148
	v_lshlrev_b32_e32 v252, 16, v150
	v_and_b32_e32 v253, 0xffff0000, v150
	v_lshlrev_b32_e32 v250, 16, v149
	v_and_b32_e32 v251, 0xffff0000, v149
	v_lshlrev_b32_e32 v254, 16, v151
	v_and_b32_e32 v255, 0xffff0000, v151
	v_pk_add_f32 v[248:249], v[248:249], v[252:253]
	v_pk_add_f32 v[250:251], v[250:251], v[254:255]
	v_pk_add_f32 v[128:129], v[128:129], v[248:249]
	v_pk_add_f32 v[130:131], v[130:131], v[250:251]
	v_cvt_pk_bf16_f32 v148, v128, v129
	v_cvt_pk_bf16_f32 v149, v130, v131
	v_lshlrev_b32_e32 v248, 16, v148
	v_and_b32_e32 v249, 0xffff0000, v148
	v_lshlrev_b32_e32 v250, 16, v149
	v_and_b32_e32 v251, 0xffff0000, v149
	v_pk_add_f32 v[128:129], v[128:129], v[248:249] neg_lo:[0,1] neg_hi:[0,1]
	v_pk_add_f32 v[130:131], v[130:131], v[250:251] neg_lo:[0,1] neg_hi:[0,1]
	v_cvt_pk_bf16_f32 v150, v128, v129
	v_cvt_pk_bf16_f32 v151, v130, v131
	global_store_dwordx2 v244, v[148:149], s[44:45]
	global_store_dwordx2 v244, v[150:151], s[50:51]
	global_load_dwordx2 v[148:149], v245, s[44:45] offset:64
	global_load_dwordx2 v[150:151], v245, s[50:51] offset:64
	ds_bpermute_b32 v72, v15, v72
	ds_bpermute_b32 v73, v15, v73
	ds_bpermute_b32 v74, v15, v74
	ds_bpermute_b32 v75, v15, v75
	s_waitcnt vmcnt(20)
	s_waitcnt lgkmcnt(8)
	v_lshlrev_b32_e32 v248, 16, v152
	v_and_b32_e32 v249, 0xffff0000, v152
	v_lshlrev_b32_e32 v252, 16, v154
	v_and_b32_e32 v253, 0xffff0000, v154
	v_lshlrev_b32_e32 v250, 16, v153
	v_and_b32_e32 v251, 0xffff0000, v153
	v_lshlrev_b32_e32 v254, 16, v155
	v_and_b32_e32 v255, 0xffff0000, v155
	v_pk_add_f32 v[248:249], v[248:249], v[252:253]
	v_pk_add_f32 v[250:251], v[250:251], v[254:255]
	v_pk_add_f32 v[112:113], v[112:113], v[248:249]
	v_pk_add_f32 v[114:115], v[114:115], v[250:251]
	v_cvt_pk_bf16_f32 v152, v112, v113
	v_cvt_pk_bf16_f32 v153, v114, v115
	v_lshlrev_b32_e32 v248, 16, v152
	v_and_b32_e32 v249, 0xffff0000, v152
	v_lshlrev_b32_e32 v250, 16, v153
	v_and_b32_e32 v251, 0xffff0000, v153
	v_pk_add_f32 v[112:113], v[112:113], v[248:249] neg_lo:[0,1] neg_hi:[0,1]
	v_pk_add_f32 v[114:115], v[114:115], v[250:251] neg_lo:[0,1] neg_hi:[0,1]
	v_cvt_pk_bf16_f32 v154, v112, v113
	v_cvt_pk_bf16_f32 v155, v114, v115
	global_store_dwordx2 v244, v[152:153], s[44:45] offset:32
	global_store_dwordx2 v244, v[154:155], s[50:51] offset:32
	global_load_dwordx2 v[152:153], v245, s[44:45] offset:96
	global_load_dwordx2 v[154:155], v245, s[50:51] offset:96
	ds_bpermute_b32 v124, v15, v124
	ds_bpermute_b32 v125, v15, v125
	ds_bpermute_b32 v126, v15, v126
	ds_bpermute_b32 v127, v15, v127
	s_waitcnt vmcnt(20)
	s_waitcnt lgkmcnt(8)
	v_lshlrev_b32_e32 v248, 16, v156
	v_and_b32_e32 v249, 0xffff0000, v156
	v_lshlrev_b32_e32 v252, 16, v158
	v_and_b32_e32 v253, 0xffff0000, v158
	v_lshlrev_b32_e32 v250, 16, v157
	v_and_b32_e32 v251, 0xffff0000, v157
	v_lshlrev_b32_e32 v254, 16, v159
	v_and_b32_e32 v255, 0xffff0000, v159
	v_pk_add_f32 v[248:249], v[248:249], v[252:253]
	v_pk_add_f32 v[250:251], v[250:251], v[254:255]
	v_pk_add_f32 v[92:93], v[92:93], v[248:249]
	v_pk_add_f32 v[94:95], v[94:95], v[250:251]
	v_cvt_pk_bf16_f32 v156, v92, v93
	v_cvt_pk_bf16_f32 v157, v94, v95
	v_lshlrev_b32_e32 v248, 16, v156
	v_and_b32_e32 v249, 0xffff0000, v156
	v_lshlrev_b32_e32 v250, 16, v157
	v_and_b32_e32 v251, 0xffff0000, v157
	v_pk_add_f32 v[92:93], v[92:93], v[248:249] neg_lo:[0,1] neg_hi:[0,1]
	v_pk_add_f32 v[94:95], v[94:95], v[250:251] neg_lo:[0,1] neg_hi:[0,1]
	v_cvt_pk_bf16_f32 v158, v92, v93
	v_cvt_pk_bf16_f32 v159, v94, v95
	global_store_dwordx2 v244, v[156:157], s[44:45] offset:64
	global_store_dwordx2 v244, v[158:159], s[50:51] offset:64
	ds_bpermute_b32 v104, v15, v104
	ds_bpermute_b32 v105, v15, v105
	ds_bpermute_b32 v106, v15, v106
	ds_bpermute_b32 v107, v15, v107
	s_waitcnt vmcnt(18)
	s_waitcnt lgkmcnt(8)
; __device__ __forceinline__ float bflo(unsigned v) { return __uint_as_float(v << 16); }
; __device__ __forceinline__ float bfhi(unsigned v) { return __uint_as_float(v & 0xffff0000u); }
; template <int EPI, int TI>
; __device__ __forceinline__ void gemm_epilogue(const WS& ws, const f32x4 (&acc)[4][TI], const float (&rs)[TI], int tok0, int n0,
;                                               int wm, int wn, int lr, int lq, bool dry) {
;     ...
;   } else {
; #pragma unroll
;     for (int ni = 0; ni < 4; ++ni)
; #pragma unroll
;       for (int ti = 0; ti < TI; ++ti) {
;         if (!(ti < 4 || (lr == 0 && (ni >> 1) == wn))) continue;
;         const size_t off = (size_t)(ti < 4 ? tokr(ti) : tok0 + 128) * 1024 + nw + ni * 16 + 4 * lq;
;         const u32x2 hi = *(const u32x2*)(ws.HHI + off), lo = *(const u32x2*)(ws.HLO + off);
;         const float h0 = bflo(hi.x) + bflo(lo.x) + acc[ni][ti][0], h1 = bfhi(hi.x) + bfhi(lo.x) + acc[ni][ti][1];
;         const float h2 = bflo(hi.y) + bflo(lo.y) + acc[ni][ti][2], h3 = bfhi(hi.y) + bfhi(lo.y) + acc[ni][ti][3];
;         u32x2 nh; nh.x = cvt_pk_bf16(h0, h1); nh.y = cvt_pk_bf16(h2, h3);
;         u32x2 nl; nl.x = cvt_pk_bf16(h0 - bflo(nh.x), h1 - bfhi(nh.x)); nl.y = cvt_pk_bf16(h2 - bflo(nh.y), h3 - bfhi(nh.y));
;         if (!dry) { *(u32x2*)(ws.HHI + off) = nh; *(u32x2*)(ws.HLO + off) = nl; }
;       }
	v_lshlrev_b32_e32 v248, 16, v160
	v_and_b32_e32 v249, 0xffff0000, v160
	v_lshlrev_b32_e32 v252, 16, v162
	v_and_b32_e32 v253, 0xffff0000, v162
	v_lshlrev_b32_e32 v250, 16, v161
	v_and_b32_e32 v251, 0xffff0000, v161
	v_lshlrev_b32_e32 v254, 16, v163
	v_and_b32_e32 v255, 0xffff0000, v163
	v_pk_add_f32 v[248:249], v[248:249], v[252:253]
	v_pk_add_f32 v[250:251], v[250:251], v[254:255]
	v_pk_add_f32 v[72:73], v[72:73], v[248:249]
	v_pk_add_f32 v[74:75], v[74:75], v[250:251]
	v_cvt_pk_bf16_f32 v160, v72, v73
	v_cvt_pk_bf16_f32 v161, v74, v75
	v_lshlrev_b32_e32 v248, 16, v160
	v_and_b32_e32 v249, 0xffff0000, v160
	v_lshlrev_b32_e32 v250, 16, v161
	v_and_b32_e32 v251, 0xffff0000, v161
	v_pk_add_f32 v[72:73], v[72:73], v[248:249] neg_lo:[0,1] neg_hi:[0,1]
	v_pk_add_f32 v[74:75], v[74:75], v[250:251] neg_lo:[0,1] neg_hi:[0,1]
	v_cvt_pk_bf16_f32 v162, v72, v73
	v_cvt_pk_bf16_f32 v163, v74, v75
	global_store_dwordx2 v244, v[160:161], s[44:45] offset:96
	global_store_dwordx2 v244, v[162:163], s[50:51] offset:96
	ds_bpermute_b32 v84, v15, v84
	ds_bpermute_b32 v85, v15, v85
	ds_bpermute_b32 v86, v15, v86
	ds_bpermute_b32 v87, v15, v87
	s_waitcnt vmcnt(16)
	s_waitcnt lgkmcnt(8)
	v_lshlrev_b32_e32 v248, 16, v140
	v_and_b32_e32 v249, 0xffff0000, v140
	v_lshlrev_b32_e32 v252, 16, v142
	v_and_b32_e32 v253, 0xffff0000, v142
	v_lshlrev_b32_e32 v250, 16, v141
	v_and_b32_e32 v251, 0xffff0000, v141
	v_lshlrev_b32_e32 v254, 16, v143
	v_and_b32_e32 v255, 0xffff0000, v143
	v_pk_add_f32 v[248:249], v[248:249], v[252:253]
	v_pk_add_f32 v[250:251], v[250:251], v[254:255]
	v_pk_add_f32 v[124:125], v[124:125], v[248:249]
	v_pk_add_f32 v[126:127], v[126:127], v[250:251]
	v_cvt_pk_bf16_f32 v140, v124, v125
	v_cvt_pk_bf16_f32 v141, v126, v127
	v_lshlrev_b32_e32 v248, 16, v140
	v_and_b32_e32 v249, 0xffff0000, v140
	v_lshlrev_b32_e32 v250, 16, v141
	v_and_b32_e32 v251, 0xffff0000, v141
	v_pk_add_f32 v[124:125], v[124:125], v[248:249] neg_lo:[0,1] neg_hi:[0,1]
	v_pk_add_f32 v[126:127], v[126:127], v[250:251] neg_lo:[0,1] neg_hi:[0,1]
	v_cvt_pk_bf16_f32 v142, v124, v125
	v_cvt_pk_bf16_f32 v143, v126, v127
	global_store_dwordx2 v245, v[140:141], s[44:45]
	global_store_dwordx2 v245, v[142:143], s[50:51]
	ds_bpermute_b32 v68, v15, v68
	ds_bpermute_b32 v69, v15, v69
	ds_bpermute_b32 v70, v15, v70
	ds_bpermute_b32 v71, v15, v71
	s_waitcnt vmcnt(14)
	s_waitcnt lgkmcnt(8)
	v_lshlrev_b32_e32 v248, 16, v144
	v_and_b32_e32 v249, 0xffff0000, v144
	v_lshlrev_b32_e32 v252, 16, v146
	v_and_b32_e32 v253, 0xffff0000, v146
	v_lshlrev_b32_e32 v250, 16, v145
	v_and_b32_e32 v251, 0xffff0000, v145
	v_lshlrev_b32_e32 v254, 16, v147
	v_and_b32_e32 v255, 0xffff0000, v147
	v_pk_add_f32 v[248:249], v[248:249], v[252:253]
	v_pk_add_f32 v[250:251], v[250:251], v[254:255]
	v_pk_add_f32 v[104:105], v[104:105], v[248:249]
	v_pk_add_f32 v[106:107], v[106:107], v[250:251]
	v_cvt_pk_bf16_f32 v144, v104, v105
	v_cvt_pk_bf16_f32 v145, v106, v107
	v_lshlrev_b32_e32 v248, 16, v144
	v_and_b32_e32 v249, 0xffff0000, v144
	v_lshlrev_b32_e32 v250, 16, v145
	v_and_b32_e32 v251, 0xffff0000, v145
	v_pk_add_f32 v[104:105], v[104:105], v[248:249] neg_lo:[0,1] neg_hi:[0,1]
	v_pk_add_f32 v[106:107], v[106:107], v[250:251] neg_lo:[0,1] neg_hi:[0,1]
	v_cvt_pk_bf16_f32 v146, v104, v105
	v_cvt_pk_bf16_f32 v147, v106, v107
	global_store_dwordx2 v245, v[144:145], s[44:45] offset:32
	global_store_dwordx2 v245, v[146:147], s[50:51] offset:32
	s_waitcnt vmcnt(12)
	s_waitcnt lgkmcnt(4)
	v_lshlrev_b32_e32 v248, 16, v148
	v_and_b32_e32 v249, 0xffff0000, v148
	v_lshlrev_b32_e32 v252, 16, v150
	v_and_b32_e32 v253, 0xffff0000, v150
	v_lshlrev_b32_e32 v250, 16, v149
	v_and_b32_e32 v251, 0xffff0000, v149
	v_lshlrev_b32_e32 v254, 16, v151
	v_and_b32_e32 v255, 0xffff0000, v151
	v_pk_add_f32 v[248:249], v[248:249], v[252:253]
	v_pk_add_f32 v[250:251], v[250:251], v[254:255]
	v_pk_add_f32 v[84:85], v[84:85], v[248:249]
	v_pk_add_f32 v[86:87], v[86:87], v[250:251]
	v_cvt_pk_bf16_f32 v148, v84, v85
	v_cvt_pk_bf16_f32 v149, v86, v87
	v_lshlrev_b32_e32 v248, 16, v148
	v_and_b32_e32 v249, 0xffff0000, v148
	v_lshlrev_b32_e32 v250, 16, v149
	v_and_b32_e32 v251, 0xffff0000, v149
	v_pk_add_f32 v[84:85], v[84:85], v[248:249] neg_lo:[0,1] neg_hi:[0,1]
	v_pk_add_f32 v[86:87], v[86:87], v[250:251] neg_lo:[0,1] neg_hi:[0,1]
	v_cvt_pk_bf16_f32 v150, v84, v85
	v_cvt_pk_bf16_f32 v151, v86, v87
	global_store_dwordx2 v245, v[148:149], s[44:45] offset:64
	global_store_dwordx2 v245, v[150:151], s[50:51] offset:64
	s_waitcnt vmcnt(10)
	s_waitcnt lgkmcnt(0)
; __device__ __forceinline__ float bflo(unsigned v) { return __uint_as_float(v << 16); }
; __device__ __forceinline__ float bfhi(unsigned v) { return __uint_as_float(v & 0xffff0000u); }
; template <int EPI, int TI>
; __device__ __forceinline__ void gemm_epilogue(const WS& ws, const f32x4 (&acc)[4][TI], const float (&rs)[TI], int tok0, int n0,
;                                               int wm, int wn, int lr, int lq, bool dry) {
;     ...
;   } else {
; #pragma unroll
;     for (int ni = 0; ni < 4; ++ni)
; #pragma unroll
;       for (int ti = 0; ti < TI; ++ti) {
;         if (!(ti < 4 || (lr == 0 && (ni >> 1) == wn))) continue;
;         const size_t off = (size_t)(ti < 4 ? tokr(ti) : tok0 + 128) * 1024 + nw + ni * 16 + 4 * lq;
;         const u32x2 hi = *(const u32x2*)(ws.HHI + off), lo = *(const u32x2*)(ws.HLO + off);
;         const float h0 = bflo(hi.x) + bflo(lo.x) + acc[ni][ti][0], h1 = bfhi(hi.x) + bfhi(lo.x) + acc[ni][ti][1];
;         const float h2 = bflo(hi.y) + bflo(lo.y) + acc[ni][ti][2], h3 = bfhi(hi.y) + bfhi(lo.y) + acc[ni][ti][3];
;         u32x2 nh; nh.x = cvt_pk_bf16(h0, h1); nh.y = cvt_pk_bf16(h2, h3);
;         u32x2 nl; nl.x = cvt_pk_bf16(h0 - bflo(nh.x), h1 - bfhi(nh.x)); nl.y = cvt_pk_bf16(h2 - bflo(nh.y), h3 - bfhi(nh.y));
;         if (!dry) { *(u32x2*)(ws.HHI + off) = nh; *(u32x2*)(ws.HLO + off) = nl; }
;       }
	v_lshlrev_b32_e32 v248, 16, v152
	v_and_b32_e32 v249, 0xffff0000, v152
	v_lshlrev_b32_e32 v252, 16, v154
	v_and_b32_e32 v253, 0xffff0000, v154
	v_lshlrev_b32_e32 v250, 16, v153
	v_and_b32_e32 v251, 0xffff0000, v153
	v_lshlrev_b32_e32 v254, 16, v155
	v_and_b32_e32 v255, 0xffff0000, v155
	v_pk_add_f32 v[248:249], v[248:249], v[252:253]
	v_pk_add_f32 v[250:251], v[250:251], v[254:255]
	v_pk_add_f32 v[68:69], v[68:69], v[248:249]
	v_pk_add_f32 v[70:71], v[70:71], v[250:251]
	v_cvt_pk_bf16_f32 v152, v68, v69
	v_cvt_pk_bf16_f32 v153, v70, v71
	v_lshlrev_b32_e32 v248, 16, v152
	v_and_b32_e32 v249, 0xffff0000, v152
	v_lshlrev_b32_e32 v250, 16, v153
	v_and_b32_e32 v251, 0xffff0000, v153
	v_pk_add_f32 v[68:69], v[68:69], v[248:249] neg_lo:[0,1] neg_hi:[0,1]
	v_pk_add_f32 v[70:71], v[70:71], v[250:251] neg_lo:[0,1] neg_hi:[0,1]
	v_cvt_pk_bf16_f32 v154, v68, v69
	v_cvt_pk_bf16_f32 v155, v70, v71
	global_store_dwordx2 v245, v[152:153], s[44:45] offset:96
	global_store_dwordx2 v245, v[154:155], s[50:51] offset:96
	s_and_b64 exec, s[6:7], s[42:43]
	s_waitcnt vmcnt(63)
	v_lshlrev_b32_e32 v248, 16, v204
	v_and_b32_e32 v249, 0xffff0000, v204
	v_lshlrev_b32_e32 v252, 16, v206
	v_and_b32_e32 v253, 0xffff0000, v206
	v_lshlrev_b32_e32 v250, 16, v205
	v_and_b32_e32 v251, 0xffff0000, v205
	v_lshlrev_b32_e32 v254, 16, v207
	v_and_b32_e32 v255, 0xffff0000, v207
	v_pk_add_f32 v[248:249], v[248:249], v[252:253]
	v_pk_add_f32 v[250:251], v[250:251], v[254:255]
	v_pk_add_f32 v[108:109], v[108:109], v[248:249]
	v_pk_add_f32 v[110:111], v[110:111], v[250:251]
	v_cvt_pk_bf16_f32 v204, v108, v109
	v_cvt_pk_bf16_f32 v205, v110, v111
	v_lshlrev_b32_e32 v248, 16, v204
	v_and_b32_e32 v249, 0xffff0000, v204
	v_lshlrev_b32_e32 v250, 16, v205
	v_and_b32_e32 v251, 0xffff0000, v205
	v_pk_add_f32 v[108:109], v[108:109], v[248:249] neg_lo:[0,1] neg_hi:[0,1]
	v_pk_add_f32 v[110:111], v[110:111], v[250:251] neg_lo:[0,1] neg_hi:[0,1]
	v_cvt_pk_bf16_f32 v206, v108, v109
	v_cvt_pk_bf16_f32 v207, v110, v111
	global_store_dwordx2 v246, v[204:205], s[44:45]
	global_store_dwordx2 v246, v[206:207], s[50:51]
	s_waitcnt vmcnt(63)
	v_lshlrev_b32_e32 v248, 16, v208
	v_and_b32_e32 v249, 0xffff0000, v208
	v_lshlrev_b32_e32 v252, 16, v210
	v_and_b32_e32 v253, 0xffff0000, v210
	v_lshlrev_b32_e32 v250, 16, v209
	v_and_b32_e32 v251, 0xffff0000, v209
	v_lshlrev_b32_e32 v254, 16, v211
	v_and_b32_e32 v255, 0xffff0000, v211
	v_pk_add_f32 v[248:249], v[248:249], v[252:253]
	v_pk_add_f32 v[250:251], v[250:251], v[254:255]
	v_pk_add_f32 v[88:89], v[88:89], v[248:249]
	v_pk_add_f32 v[90:91], v[90:91], v[250:251]
	v_cvt_pk_bf16_f32 v208, v88, v89
	v_cvt_pk_bf16_f32 v209, v90, v91
	v_lshlrev_b32_e32 v248, 16, v208
	v_and_b32_e32 v249, 0xffff0000, v208
	v_lshlrev_b32_e32 v250, 16, v209
	v_and_b32_e32 v251, 0xffff0000, v209
	v_pk_add_f32 v[88:89], v[88:89], v[248:249] neg_lo:[0,1] neg_hi:[0,1]
	v_pk_add_f32 v[90:91], v[90:91], v[250:251] neg_lo:[0,1] neg_hi:[0,1]
	v_cvt_pk_bf16_f32 v210, v88, v89
	v_cvt_pk_bf16_f32 v211, v90, v91
	global_store_dwordx2 v246, v[208:209], s[44:45] offset:32
	global_store_dwordx2 v246, v[210:211], s[50:51] offset:32
	s_and_b64 exec, s[6:7], s[52:53]
	s_waitcnt vmcnt(63)
	v_lshlrev_b32_e32 v248, 16, v212
	v_and_b32_e32 v249, 0xffff0000, v212
	v_lshlrev_b32_e32 v252, 16, v214
	v_and_b32_e32 v253, 0xffff0000, v214
	v_lshlrev_b32_e32 v250, 16, v213
	v_and_b32_e32 v251, 0xffff0000, v213
	v_lshlrev_b32_e32 v254, 16, v215
	v_and_b32_e32 v255, 0xffff0000, v215
	v_pk_add_f32 v[248:249], v[248:249], v[252:253]
	v_pk_add_f32 v[250:251], v[250:251], v[254:255]
	v_pk_add_f32 v[36:37], v[36:37], v[248:249]
	v_pk_add_f32 v[38:39], v[38:39], v[250:251]
	v_cvt_pk_bf16_f32 v212, v36, v37
	v_cvt_pk_bf16_f32 v213, v38, v39
	v_lshlrev_b32_e32 v248, 16, v212
	v_and_b32_e32 v249, 0xffff0000, v212
	v_lshlrev_b32_e32 v250, 16, v213
	v_and_b32_e32 v251, 0xffff0000, v213
	v_pk_add_f32 v[36:37], v[36:37], v[248:249] neg_lo:[0,1] neg_hi:[0,1]
	v_pk_add_f32 v[38:39], v[38:39], v[250:251] neg_lo:[0,1] neg_hi:[0,1]
	v_cvt_pk_bf16_f32 v214, v36, v37
	v_cvt_pk_bf16_f32 v215, v38, v39
	global_store_dwordx2 v246, v[212:213], s[44:45] offset:64
	global_store_dwordx2 v246, v[214:215], s[50:51] offset:64
	s_waitcnt vmcnt(63)
	v_lshlrev_b32_e32 v248, 16, v216
	v_and_b32_e32 v249, 0xffff0000, v216
	v_lshlrev_b32_e32 v252, 16, v218
	v_and_b32_e32 v253, 0xffff0000, v218
	v_lshlrev_b32_e32 v250, 16, v217
	v_and_b32_e32 v251, 0xffff0000, v217
	v_lshlrev_b32_e32 v254, 16, v219
	v_and_b32_e32 v255, 0xffff0000, v219
	v_pk_add_f32 v[248:249], v[248:249], v[252:253]
	v_pk_add_f32 v[250:251], v[250:251], v[254:255]
	v_pk_add_f32 v[8:9], v[8:9], v[248:249]
	v_pk_add_f32 v[10:11], v[10:11], v[250:251]
	v_cvt_pk_bf16_f32 v216, v8, v9
	v_cvt_pk_bf16_f32 v217, v10, v11
	v_lshlrev_b32_e32 v248, 16, v216
	v_and_b32_e32 v249, 0xffff0000, v216
	v_lshlrev_b32_e32 v250, 16, v217
	v_and_b32_e32 v251, 0xffff0000, v217
	v_pk_add_f32 v[8:9], v[8:9], v[248:249] neg_lo:[0,1] neg_hi:[0,1]
	v_pk_add_f32 v[10:11], v[10:11], v[250:251] neg_lo:[0,1] neg_hi:[0,1]
	v_cvt_pk_bf16_f32 v218, v8, v9
	v_cvt_pk_bf16_f32 v219, v10, v11
	global_store_dwordx2 v246, v[216:217], s[44:45] offset:96
	global_store_dwordx2 v246, v[218:219], s[50:51] offset:96
	s_mov_b64 exec, s[6:7]
